# S5 output GEMM epilogue: d_skip loaded once, u prefetched two blocks ahead, stores parked in dead acc regs and issued at the end
# speedup vs baseline: 1.0602x; 1.0023x over previous
.LBB0_354:
	s_and_b64 vcc, exec, s[42:43]
	s_cbranch_vccz .LBB0_356
	s_ashr_i32 s6, s66, 6
	v_mov_b64_e32 v[132:133], s[94:95]
	s_and_b32 s6, s6, -16
	v_mad_i64_i32 v[128:129], s[42:43], v168, s69, v[132:133]
	v_lshlrev_b32_e32 v144, 1, v156
	s_ashr_i32 s7, s6, 31
	v_lshlrev_b32_e32 v130, 4, v168
	v_lshl_add_u64 v[136:137], v[128:129], 0, v[144:145]
	v_lshl_add_u64 v[134:135], s[6:7], 2, v[160:161]
	v_and_b32_e32 v140, 0x3cf0, v130
	v_lshlrev_b32_e32 v210, 1, v156
	v_mov_b32_e32 v211, 0
	v_lshl_add_u64 v[210:211], s[94:95], 0, v[210:211]
	global_load_dwordx4 v[202:205], v[134:135], off offset:16
	global_load_dwordx4 v[206:209], v[134:135], off
	v_mad_i64_i32 v[212:213], vcc, v168, s69, v[210:211]
	global_load_dwordx4 v[190:193], v[212:213], off
	v_mad_i64_i32 v[212:213], vcc, v168, s69, v[210:211]
	global_load_dwordx4 v[194:197], v[212:213], off offset:256
	s_lshl_b64 s[6:7], s[6:7], 1
	v_mov_b32_e32 v167, v145
	s_waitcnt vmcnt(1)
	v_mov_b32_e32 v128, v190
	v_mov_b32_e32 v129, v191
	v_mov_b32_e32 v130, v192
	v_mov_b32_e32 v131, v193
	v_mov_b32_e32 v170, v202
	v_mov_b32_e32 v171, v203
	v_mov_b32_e32 v172, v204
	v_mov_b32_e32 v173, v205
	v_mov_b32_e32 v174, v206
	v_mov_b32_e32 v175, v207
	v_mov_b32_e32 v176, v208
	v_mov_b32_e32 v177, v209
	v_add_u32_e32 v214, 0x10, v168
	v_mad_i64_i32 v[212:213], vcc, v214, s69, v[210:211]
	global_load_dwordx4 v[198:201], v[212:213], off
	v_lshlrev_b32_e32 v138, 16, v128
	v_and_b32_e32 v139, 0xffff0000, v128
	v_pk_fma_f32 v[138:139], v[174:175], v[138:139], v[124:125]
	s_nop 0
	v_mul_f32_e32 v128, 0x3d372713, v138
	v_mul_f32_e32 v128, v138, v128
	v_fma_f32 v128, v138, v128, v138
	v_mul_f32_e32 v128, 0x3fcc422a, v128
	v_mul_f32_e32 v128, 0xbfb8aa3b, v128
	v_exp_f32_e32 v128, v128
	s_nop 0
	v_add_f32_e32 v128, 1.0, v128
	v_rcp_f32_e32 v142, v128
	v_mul_f32_e32 v128, 0x3d372713, v139
	v_mul_f32_e32 v128, v139, v128
	v_fma_f32 v128, v139, v128, v139
	v_mul_f32_e32 v128, 0x3fcc422a, v128
	v_mul_f32_e32 v128, 0xbfb8aa3b, v128
	v_exp_f32_e32 v128, v128
	s_nop 0
	v_add_f32_e32 v128, 1.0, v128
	v_rcp_f32_e32 v143, v128
	v_lshlrev_b32_e32 v128, 16, v129
	v_and_b32_e32 v129, 0xffff0000, v129
	v_pk_fma_f32 v[128:129], v[176:177], v[128:129], v[126:127]
	v_pk_mul_f32 v[138:139], v[138:139], v[142:143]
	v_mul_f32_e32 v141, 0x3d372713, v128
	v_mul_f32_e32 v141, v128, v141
	v_fma_f32 v141, v128, v141, v128
	v_mul_f32_e32 v141, 0x3fcc422a, v141
	v_mul_f32_e32 v141, 0xbfb8aa3b, v141
	v_exp_f32_e32 v141, v141
	s_nop 0
	v_add_f32_e32 v141, 1.0, v141
	v_rcp_f32_e32 v142, v141
	v_mul_f32_e32 v141, 0x3d372713, v129
	v_mul_f32_e32 v141, v129, v141
	v_fma_f32 v141, v129, v141, v129
	v_mul_f32_e32 v141, 0x3fcc422a, v141
	v_mul_f32_e32 v141, 0xbfb8aa3b, v141
	v_exp_f32_e32 v141, v141
	s_nop 0
	v_add_f32_e32 v141, 1.0, v141
	v_rcp_f32_e32 v143, v141
	s_nop 0
	v_pk_mul_f32 v[142:143], v[128:129], v[142:143]
	v_lshlrev_b32_e32 v128, 16, v130
	v_and_b32_e32 v129, 0xffff0000, v130
	v_pk_fma_f32 v[128:129], v[170:171], v[128:129], v[120:121]
	s_nop 0
	v_mul_f32_e32 v130, 0x3d372713, v128
	v_mul_f32_e32 v130, v128, v130
	v_fma_f32 v130, v128, v130, v128
	v_mul_f32_e32 v130, 0x3fcc422a, v130
	v_mul_f32_e32 v130, 0xbfb8aa3b, v130
	v_exp_f32_e32 v130, v130
	s_nop 0
	v_add_f32_e32 v130, 1.0, v130
	v_rcp_f32_e32 v170, v130
	v_mul_f32_e32 v130, 0x3d372713, v129
	v_mul_f32_e32 v130, v129, v130
	v_fma_f32 v130, v129, v130, v129
	v_mul_f32_e32 v130, 0x3fcc422a, v130
	v_mul_f32_e32 v130, 0xbfb8aa3b, v130
	v_exp_f32_e32 v130, v130
	s_nop 0
	v_add_f32_e32 v130, 1.0, v130
	v_rcp_f32_e32 v171, v130
	s_nop 0
	v_pk_mul_f32 v[170:171], v[128:129], v[170:171]
	v_lshlrev_b32_e32 v128, 16, v131
	v_and_b32_e32 v129, 0xffff0000, v131
	v_pk_fma_f32 v[128:129], v[172:173], v[128:129], v[122:123]
	s_nop 0
	v_mul_f32_e32 v130, 0x3d372713, v128
	v_mul_f32_e32 v131, 0x3d372713, v129
	v_mul_f32_e32 v130, v128, v130
	v_mul_f32_e32 v131, v129, v131
	v_fma_f32 v130, v128, v130, v128
	v_fma_f32 v131, v129, v131, v129
	v_mul_f32_e32 v130, 0x3fcc422a, v130
	v_mul_f32_e32 v131, 0x3fcc422a, v131
	v_mul_f32_e32 v130, 0xbfb8aa3b, v130
	v_mul_f32_e32 v131, 0xbfb8aa3b, v131
	v_exp_f32_e32 v130, v130
	v_exp_f32_e32 v131, v131
	v_add_f32_e32 v130, 1.0, v130
	v_add_f32_e32 v131, 1.0, v131
	v_rcp_f32_e32 v130, v130
	v_rcp_f32_e32 v131, v131
	s_nop 0
	v_pk_mul_f32 v[172:173], v[128:129], v[130:131]
	v_cvt_pk_bf16_f32 v128, v138, v139
	v_or_b32_e32 v138, v140, v186
	v_lshlrev_b32_e32 v138, 11, v138
	v_mov_b32_e32 v139, v145
	v_lshl_add_u64 v[138:139], s[90:91], 0, v[138:139]
	v_lshl_add_u64 v[138:139], v[138:139], 0, s[6:7]
	v_cvt_pk_bf16_f32 v129, v142, v143
	v_cvt_pk_bf16_f32 v130, v170, v171
	v_cvt_pk_bf16_f32 v131, v172, v173
	v_lshl_add_u64 v[138:139], v[138:139], 0, v[166:167]
	v_mov_b32_e32 v120, v128
	v_mov_b32_e32 v121, v129
	v_mov_b32_e32 v122, v130
	v_mov_b32_e32 v123, v131
	v_mov_b32_e32 v124, v138
	v_mov_b32_e32 v125, v139
	s_waitcnt vmcnt(1)
	v_mov_b32_e32 v128, v194
	v_mov_b32_e32 v129, v195
	v_mov_b32_e32 v130, v196
	v_mov_b32_e32 v131, v197
	v_add_u32_e32 v214, 0x10, v168
	v_mad_i64_i32 v[212:213], vcc, v214, s69, v[210:211]
	global_load_dwordx4 v[190:193], v[212:213], off offset:256
	v_lshlrev_b32_e32 v142, 16, v128
	v_and_b32_e32 v143, 0xffff0000, v128
	v_mov_b32_e32 v136, v202
	v_mov_b32_e32 v137, v203
	v_mov_b32_e32 v138, v204
	v_mov_b32_e32 v139, v205
	v_mov_b32_e32 v170, v206
	v_mov_b32_e32 v171, v207
	v_mov_b32_e32 v172, v208
	v_mov_b32_e32 v173, v209
	v_pk_fma_f32 v[142:143], v[170:171], v[142:143], v[108:109]
	s_nop 0
	v_mul_f32_e32 v128, 0x3d372713, v142
	v_mul_f32_e32 v128, v142, v128
	v_fma_f32 v128, v142, v128, v142
	v_mul_f32_e32 v128, 0x3fcc422a, v128
	v_mul_f32_e32 v128, 0xbfb8aa3b, v128
	v_exp_f32_e32 v128, v128
	s_nop 0
	v_add_f32_e32 v128, 1.0, v128
	v_rcp_f32_e32 v170, v128
	v_mul_f32_e32 v128, 0x3d372713, v143
	v_mul_f32_e32 v128, v143, v128
	v_fma_f32 v128, v143, v128, v143
	v_mul_f32_e32 v128, 0x3fcc422a, v128
	v_mul_f32_e32 v128, 0xbfb8aa3b, v128
	v_exp_f32_e32 v128, v128
	s_nop 0
	v_add_f32_e32 v128, 1.0, v128
	v_rcp_f32_e32 v171, v128
	v_lshlrev_b32_e32 v128, 16, v129
	v_and_b32_e32 v129, 0xffff0000, v129
	v_pk_fma_f32 v[128:129], v[172:173], v[128:129], v[110:111]
	v_pk_mul_f32 v[142:143], v[142:143], v[170:171]
	v_mul_f32_e32 v141, 0x3d372713, v128
	v_mul_f32_e32 v141, v128, v141
	v_fma_f32 v141, v128, v141, v128
	v_mul_f32_e32 v141, 0x3fcc422a, v141
	v_mul_f32_e32 v141, 0xbfb8aa3b, v141
	v_exp_f32_e32 v141, v141
	s_nop 0
	v_add_f32_e32 v141, 1.0, v141
	v_rcp_f32_e32 v170, v141
	v_mul_f32_e32 v141, 0x3d372713, v129
	v_mul_f32_e32 v141, v129, v141
	v_fma_f32 v141, v129, v141, v129
	v_mul_f32_e32 v141, 0x3fcc422a, v141
	v_mul_f32_e32 v141, 0xbfb8aa3b, v141
	v_exp_f32_e32 v141, v141
	s_nop 0
	v_add_f32_e32 v141, 1.0, v141
	v_rcp_f32_e32 v171, v141
	s_nop 0
	v_pk_mul_f32 v[170:171], v[128:129], v[170:171]
	v_lshlrev_b32_e32 v128, 16, v130
	v_and_b32_e32 v129, 0xffff0000, v130
	v_pk_fma_f32 v[128:129], v[136:137], v[128:129], v[104:105]
	s_nop 0
	v_mul_f32_e32 v130, 0x3d372713, v128
	v_mul_f32_e32 v130, v128, v130
	v_fma_f32 v130, v128, v130, v128
	v_mul_f32_e32 v130, 0x3fcc422a, v130
	v_mul_f32_e32 v130, 0xbfb8aa3b, v130
	v_exp_f32_e32 v130, v130
	s_nop 0
	v_add_f32_e32 v130, 1.0, v130
	v_rcp_f32_e32 v136, v130
	v_mul_f32_e32 v130, 0x3d372713, v129
	v_mul_f32_e32 v130, v129, v130
	v_fma_f32 v130, v129, v130, v129
	v_mul_f32_e32 v130, 0x3fcc422a, v130
	v_mul_f32_e32 v130, 0xbfb8aa3b, v130
	v_exp_f32_e32 v130, v130
	s_nop 0
	v_add_f32_e32 v130, 1.0, v130
	v_rcp_f32_e32 v137, v130
	s_nop 0
	v_pk_mul_f32 v[136:137], v[128:129], v[136:137]
	v_lshlrev_b32_e32 v128, 16, v131
	v_and_b32_e32 v129, 0xffff0000, v131
	v_pk_fma_f32 v[128:129], v[138:139], v[128:129], v[106:107]
	s_nop 0
	v_mul_f32_e32 v130, 0x3d372713, v128
	v_mul_f32_e32 v131, 0x3d372713, v129
	v_mul_f32_e32 v130, v128, v130
	v_mul_f32_e32 v131, v129, v131
	v_fma_f32 v130, v128, v130, v128
	v_fma_f32 v131, v129, v131, v129
	v_mul_f32_e32 v130, 0x3fcc422a, v130
	v_mul_f32_e32 v131, 0x3fcc422a, v131
	v_mul_f32_e32 v130, 0xbfb8aa3b, v130
	v_mul_f32_e32 v131, 0xbfb8aa3b, v131
	v_exp_f32_e32 v130, v130
	v_exp_f32_e32 v131, v131
	v_add_f32_e32 v130, 1.0, v130
	v_add_f32_e32 v131, 1.0, v131
	v_rcp_f32_e32 v130, v130
	v_rcp_f32_e32 v131, v131
	s_nop 0
	v_pk_mul_f32 v[138:139], v[128:129], v[130:131]
	v_cvt_pk_bf16_f32 v130, v136, v137
	v_or_b32_e32 v136, v140, v187
	v_lshlrev_b32_e32 v136, 11, v136
	v_mov_b32_e32 v137, v145
	v_lshl_add_u64 v[136:137], s[90:91], 0, v[136:137]
	v_lshl_add_u64 v[136:137], v[136:137], 0, s[6:7]
	v_cvt_pk_bf16_f32 v128, v142, v143
	v_cvt_pk_bf16_f32 v129, v170, v171
	v_cvt_pk_bf16_f32 v131, v138, v139
	v_lshl_add_u64 v[136:137], v[136:137], 0, v[166:167]
	v_mov_b32_e32 v104, v128
	v_mov_b32_e32 v105, v129
	v_mov_b32_e32 v106, v130
	v_mov_b32_e32 v107, v131
	v_mov_b32_e32 v108, v136
	v_mov_b32_e32 v109, v137
	s_nop 1
	v_or_b32_e32 v130, 16, v168
	v_mad_i64_i32 v[128:129], s[42:43], v130, s69, v[132:133]
	v_lshlrev_b32_e32 v130, 4, v130
	v_lshl_add_u64 v[136:137], v[128:129], 0, v[144:145]
	v_and_b32_e32 v140, 0x3df0, v130
	s_waitcnt vmcnt(1)
	v_mov_b32_e32 v128, v198
	v_mov_b32_e32 v129, v199
	v_mov_b32_e32 v130, v200
	v_mov_b32_e32 v131, v201
	v_add_u32_e32 v214, 0x20, v168
	v_mad_i64_i32 v[212:213], vcc, v214, s69, v[210:211]
	global_load_dwordx4 v[194:197], v[212:213], off
	v_lshlrev_b32_e32 v138, 16, v128
	v_and_b32_e32 v139, 0xffff0000, v128
	v_mov_b32_e32 v170, v202
	v_mov_b32_e32 v171, v203
	v_mov_b32_e32 v172, v204
	v_mov_b32_e32 v173, v205
	v_mov_b32_e32 v174, v206
	v_mov_b32_e32 v175, v207
	v_mov_b32_e32 v176, v208
	v_mov_b32_e32 v177, v209
	v_pk_fma_f32 v[138:139], v[174:175], v[138:139], v[116:117]
	s_nop 0
	v_mul_f32_e32 v128, 0x3d372713, v138
	v_mul_f32_e32 v128, v138, v128
	v_fma_f32 v128, v138, v128, v138
	v_mul_f32_e32 v128, 0x3fcc422a, v128
	v_mul_f32_e32 v128, 0xbfb8aa3b, v128
	v_exp_f32_e32 v128, v128
	s_nop 0
	v_add_f32_e32 v128, 1.0, v128
	v_rcp_f32_e32 v142, v128
	v_mul_f32_e32 v128, 0x3d372713, v139
	v_mul_f32_e32 v128, v139, v128
	v_fma_f32 v128, v139, v128, v139
	v_mul_f32_e32 v128, 0x3fcc422a, v128
	v_mul_f32_e32 v128, 0xbfb8aa3b, v128
	v_exp_f32_e32 v128, v128
	s_nop 0
	v_add_f32_e32 v128, 1.0, v128
	v_rcp_f32_e32 v143, v128
	v_lshlrev_b32_e32 v128, 16, v129
	v_and_b32_e32 v129, 0xffff0000, v129
	v_pk_fma_f32 v[128:129], v[176:177], v[128:129], v[118:119]
	v_pk_mul_f32 v[138:139], v[138:139], v[142:143]
	v_mul_f32_e32 v141, 0x3d372713, v128
	v_mul_f32_e32 v141, v128, v141
	v_fma_f32 v141, v128, v141, v128
	v_mul_f32_e32 v141, 0x3fcc422a, v141
	v_mul_f32_e32 v141, 0xbfb8aa3b, v141
	v_exp_f32_e32 v141, v141
	s_nop 0
	v_add_f32_e32 v141, 1.0, v141
	v_rcp_f32_e32 v142, v141
	v_mul_f32_e32 v141, 0x3d372713, v129
	v_mul_f32_e32 v141, v129, v141
	v_fma_f32 v141, v129, v141, v129
	v_mul_f32_e32 v141, 0x3fcc422a, v141
	v_mul_f32_e32 v141, 0xbfb8aa3b, v141
	v_exp_f32_e32 v141, v141
	s_nop 0
	v_add_f32_e32 v141, 1.0, v141
	v_rcp_f32_e32 v143, v141
	s_nop 0
	v_pk_mul_f32 v[142:143], v[128:129], v[142:143]
	v_lshlrev_b32_e32 v128, 16, v130
	v_and_b32_e32 v129, 0xffff0000, v130
	v_pk_fma_f32 v[128:129], v[170:171], v[128:129], v[112:113]
	s_nop 0
	v_mul_f32_e32 v130, 0x3d372713, v128
	v_mul_f32_e32 v130, v128, v130
	v_fma_f32 v130, v128, v130, v128
	v_mul_f32_e32 v130, 0x3fcc422a, v130
	v_mul_f32_e32 v130, 0xbfb8aa3b, v130
	v_exp_f32_e32 v130, v130
	s_nop 0
	v_add_f32_e32 v130, 1.0, v130
	v_rcp_f32_e32 v170, v130
	v_mul_f32_e32 v130, 0x3d372713, v129
	v_mul_f32_e32 v130, v129, v130
	v_fma_f32 v130, v129, v130, v129
	v_mul_f32_e32 v130, 0x3fcc422a, v130
	v_mul_f32_e32 v130, 0xbfb8aa3b, v130
	v_exp_f32_e32 v130, v130
	s_nop 0
	v_add_f32_e32 v130, 1.0, v130
	v_rcp_f32_e32 v171, v130
	s_nop 0
	v_pk_mul_f32 v[170:171], v[128:129], v[170:171]
	v_lshlrev_b32_e32 v128, 16, v131
	v_and_b32_e32 v129, 0xffff0000, v131
	v_pk_fma_f32 v[128:129], v[172:173], v[128:129], v[114:115]
	s_nop 0
	v_mul_f32_e32 v130, 0x3d372713, v128
	v_mul_f32_e32 v131, 0x3d372713, v129
	v_mul_f32_e32 v130, v128, v130
	v_mul_f32_e32 v131, v129, v131
	v_fma_f32 v130, v128, v130, v128
	v_fma_f32 v131, v129, v131, v129
	v_mul_f32_e32 v130, 0x3fcc422a, v130
	v_mul_f32_e32 v131, 0x3fcc422a, v131
	v_mul_f32_e32 v130, 0xbfb8aa3b, v130
	v_mul_f32_e32 v131, 0xbfb8aa3b, v131
	v_exp_f32_e32 v130, v130
	v_exp_f32_e32 v131, v131
	v_add_f32_e32 v130, 1.0, v130
	v_add_f32_e32 v131, 1.0, v131
	v_rcp_f32_e32 v130, v130
	v_rcp_f32_e32 v131, v131
	s_nop 0
	v_pk_mul_f32 v[172:173], v[128:129], v[130:131]
	v_cvt_pk_bf16_f32 v128, v138, v139
	v_or_b32_e32 v138, v140, v186
	v_lshlrev_b32_e32 v138, 11, v138
	v_mov_b32_e32 v139, v145
	v_lshl_add_u64 v[138:139], s[90:91], 0, v[138:139]
	v_lshl_add_u64 v[138:139], v[138:139], 0, s[6:7]
	v_cvt_pk_bf16_f32 v129, v142, v143
	v_cvt_pk_bf16_f32 v130, v170, v171
	v_cvt_pk_bf16_f32 v131, v172, v173
	v_lshl_add_u64 v[138:139], v[138:139], 0, v[166:167]
	v_mov_b32_e32 v112, v128
	v_mov_b32_e32 v113, v129
	v_mov_b32_e32 v114, v130
	v_mov_b32_e32 v115, v131
	v_mov_b32_e32 v116, v138
	v_mov_b32_e32 v117, v139
	s_waitcnt vmcnt(1)
	v_mov_b32_e32 v128, v190
	v_mov_b32_e32 v129, v191
	v_mov_b32_e32 v130, v192
	v_mov_b32_e32 v131, v193
	v_add_u32_e32 v214, 0x20, v168
	v_mad_i64_i32 v[212:213], vcc, v214, s69, v[210:211]
	global_load_dwordx4 v[198:201], v[212:213], off offset:256
	v_lshlrev_b32_e32 v142, 16, v128
	v_and_b32_e32 v143, 0xffff0000, v128
	v_mov_b32_e32 v136, v202
	v_mov_b32_e32 v137, v203
	v_mov_b32_e32 v138, v204
	v_mov_b32_e32 v139, v205
	v_mov_b32_e32 v170, v206
	v_mov_b32_e32 v171, v207
	v_mov_b32_e32 v172, v208
	v_mov_b32_e32 v173, v209
	v_pk_fma_f32 v[142:143], v[170:171], v[142:143], v[92:93]
	s_nop 0
	v_mul_f32_e32 v128, 0x3d372713, v142
	v_mul_f32_e32 v128, v142, v128
	v_fma_f32 v128, v142, v128, v142
	v_mul_f32_e32 v128, 0x3fcc422a, v128
	v_mul_f32_e32 v128, 0xbfb8aa3b, v128
	v_exp_f32_e32 v128, v128
	s_nop 0
	v_add_f32_e32 v128, 1.0, v128
	v_rcp_f32_e32 v170, v128
	v_mul_f32_e32 v128, 0x3d372713, v143
	v_mul_f32_e32 v128, v143, v128
	v_fma_f32 v128, v143, v128, v143
	v_mul_f32_e32 v128, 0x3fcc422a, v128
	v_mul_f32_e32 v128, 0xbfb8aa3b, v128
	v_exp_f32_e32 v128, v128
	s_nop 0
	v_add_f32_e32 v128, 1.0, v128
	v_rcp_f32_e32 v171, v128
	v_lshlrev_b32_e32 v128, 16, v129
	v_and_b32_e32 v129, 0xffff0000, v129
	v_pk_fma_f32 v[128:129], v[172:173], v[128:129], v[94:95]
	v_pk_mul_f32 v[142:143], v[142:143], v[170:171]
	v_mul_f32_e32 v141, 0x3d372713, v128
	v_mul_f32_e32 v141, v128, v141
	v_fma_f32 v141, v128, v141, v128
	v_mul_f32_e32 v141, 0x3fcc422a, v141
	v_mul_f32_e32 v141, 0xbfb8aa3b, v141
	v_exp_f32_e32 v141, v141
	s_nop 0
	v_add_f32_e32 v141, 1.0, v141
	v_rcp_f32_e32 v170, v141
	v_mul_f32_e32 v141, 0x3d372713, v129
	v_mul_f32_e32 v141, v129, v141
	v_fma_f32 v141, v129, v141, v129
	v_mul_f32_e32 v141, 0x3fcc422a, v141
	v_mul_f32_e32 v141, 0xbfb8aa3b, v141
	v_exp_f32_e32 v141, v141
	s_nop 0
	v_add_f32_e32 v141, 1.0, v141
	v_rcp_f32_e32 v171, v141
	s_nop 0
	v_pk_mul_f32 v[170:171], v[128:129], v[170:171]
	v_lshlrev_b32_e32 v128, 16, v130
	v_and_b32_e32 v129, 0xffff0000, v130
	v_pk_fma_f32 v[128:129], v[136:137], v[128:129], v[88:89]
	s_nop 0
	v_mul_f32_e32 v130, 0x3d372713, v128
	v_mul_f32_e32 v130, v128, v130
	v_fma_f32 v130, v128, v130, v128
	v_mul_f32_e32 v130, 0x3fcc422a, v130
	v_mul_f32_e32 v130, 0xbfb8aa3b, v130
	v_exp_f32_e32 v130, v130
	s_nop 0
	v_add_f32_e32 v130, 1.0, v130
	v_rcp_f32_e32 v136, v130
	v_mul_f32_e32 v130, 0x3d372713, v129
	v_mul_f32_e32 v130, v129, v130
	v_fma_f32 v130, v129, v130, v129
	v_mul_f32_e32 v130, 0x3fcc422a, v130
	v_mul_f32_e32 v130, 0xbfb8aa3b, v130
	v_exp_f32_e32 v130, v130
	s_nop 0
	v_add_f32_e32 v130, 1.0, v130
	v_rcp_f32_e32 v137, v130
	s_nop 0
	v_pk_mul_f32 v[136:137], v[128:129], v[136:137]
	v_lshlrev_b32_e32 v128, 16, v131
	v_and_b32_e32 v129, 0xffff0000, v131
	v_pk_fma_f32 v[128:129], v[138:139], v[128:129], v[90:91]
	s_nop 0
	v_mul_f32_e32 v130, 0x3d372713, v128
	v_mul_f32_e32 v131, 0x3d372713, v129
	v_mul_f32_e32 v130, v128, v130
	v_mul_f32_e32 v131, v129, v131
	v_fma_f32 v130, v128, v130, v128
	v_fma_f32 v131, v129, v131, v129
	v_mul_f32_e32 v130, 0x3fcc422a, v130
	v_mul_f32_e32 v131, 0x3fcc422a, v131
	v_mul_f32_e32 v130, 0xbfb8aa3b, v130
	v_mul_f32_e32 v131, 0xbfb8aa3b, v131
	v_exp_f32_e32 v130, v130
	v_exp_f32_e32 v131, v131
	v_add_f32_e32 v130, 1.0, v130
	v_add_f32_e32 v131, 1.0, v131
	v_rcp_f32_e32 v130, v130
	v_rcp_f32_e32 v131, v131
	s_nop 0
	v_pk_mul_f32 v[138:139], v[128:129], v[130:131]
	v_cvt_pk_bf16_f32 v130, v136, v137
	v_or_b32_e32 v136, v140, v187
	v_lshlrev_b32_e32 v136, 11, v136
	v_mov_b32_e32 v137, v145
	v_lshl_add_u64 v[136:137], s[90:91], 0, v[136:137]
	v_lshl_add_u64 v[136:137], v[136:137], 0, s[6:7]
	v_cvt_pk_bf16_f32 v128, v142, v143
	v_cvt_pk_bf16_f32 v129, v170, v171
	v_cvt_pk_bf16_f32 v131, v138, v139
	v_lshl_add_u64 v[136:137], v[136:137], 0, v[166:167]
	v_mov_b32_e32 v88, v128
	v_mov_b32_e32 v89, v129
	v_mov_b32_e32 v90, v130
	v_mov_b32_e32 v91, v131
	v_mov_b32_e32 v92, v136
	v_mov_b32_e32 v93, v137
	s_nop 1
	v_or_b32_e32 v130, 32, v168
	v_mad_i64_i32 v[128:129], s[42:43], v130, s69, v[132:133]
	v_lshlrev_b32_e32 v130, 4, v130
	v_lshl_add_u64 v[136:137], v[128:129], 0, v[144:145]
	v_and_b32_e32 v140, 0x3ef0, v130
	s_waitcnt vmcnt(1)
	v_mov_b32_e32 v128, v194
	v_mov_b32_e32 v129, v195
	v_mov_b32_e32 v130, v196
	v_mov_b32_e32 v131, v197
	v_add_u32_e32 v214, 0x30, v168
	v_mad_i64_i32 v[212:213], vcc, v214, s69, v[210:211]
	global_load_dwordx4 v[190:193], v[212:213], off
	v_lshlrev_b32_e32 v138, 16, v128
	v_and_b32_e32 v139, 0xffff0000, v128
	v_mov_b32_e32 v170, v202
	v_mov_b32_e32 v171, v203
	v_mov_b32_e32 v172, v204
	v_mov_b32_e32 v173, v205
	v_mov_b32_e32 v174, v206
	v_mov_b32_e32 v175, v207
	v_mov_b32_e32 v176, v208
	v_mov_b32_e32 v177, v209
	v_pk_fma_f32 v[138:139], v[174:175], v[138:139], v[100:101]
	s_nop 0
	v_mul_f32_e32 v128, 0x3d372713, v138
	v_mul_f32_e32 v128, v138, v128
	v_fma_f32 v128, v138, v128, v138
	v_mul_f32_e32 v128, 0x3fcc422a, v128
	v_mul_f32_e32 v128, 0xbfb8aa3b, v128
	v_exp_f32_e32 v128, v128
	s_nop 0
	v_add_f32_e32 v128, 1.0, v128
	v_rcp_f32_e32 v142, v128
	v_mul_f32_e32 v128, 0x3d372713, v139
	v_mul_f32_e32 v128, v139, v128
	v_fma_f32 v128, v139, v128, v139
	v_mul_f32_e32 v128, 0x3fcc422a, v128
	v_mul_f32_e32 v128, 0xbfb8aa3b, v128
	v_exp_f32_e32 v128, v128
	s_nop 0
	v_add_f32_e32 v128, 1.0, v128
	v_rcp_f32_e32 v143, v128
	v_lshlrev_b32_e32 v128, 16, v129
	v_and_b32_e32 v129, 0xffff0000, v129
	v_pk_fma_f32 v[128:129], v[176:177], v[128:129], v[102:103]
	v_pk_mul_f32 v[138:139], v[138:139], v[142:143]
	v_mul_f32_e32 v141, 0x3d372713, v128
	v_mul_f32_e32 v141, v128, v141
	v_fma_f32 v141, v128, v141, v128
	v_mul_f32_e32 v141, 0x3fcc422a, v141
	v_mul_f32_e32 v141, 0xbfb8aa3b, v141
	v_exp_f32_e32 v141, v141
	s_nop 0
	v_add_f32_e32 v141, 1.0, v141
	v_rcp_f32_e32 v142, v141
	v_mul_f32_e32 v141, 0x3d372713, v129
	v_mul_f32_e32 v141, v129, v141
	v_fma_f32 v141, v129, v141, v129
	v_mul_f32_e32 v141, 0x3fcc422a, v141
	v_mul_f32_e32 v141, 0xbfb8aa3b, v141
	v_exp_f32_e32 v141, v141
	s_nop 0
	v_add_f32_e32 v141, 1.0, v141
	v_rcp_f32_e32 v143, v141
	s_nop 0
	v_pk_mul_f32 v[142:143], v[128:129], v[142:143]
	v_lshlrev_b32_e32 v128, 16, v130
	v_and_b32_e32 v129, 0xffff0000, v130
	v_pk_fma_f32 v[128:129], v[170:171], v[128:129], v[96:97]
	s_nop 0
	v_mul_f32_e32 v130, 0x3d372713, v128
	v_mul_f32_e32 v130, v128, v130
	v_fma_f32 v130, v128, v130, v128
	v_mul_f32_e32 v130, 0x3fcc422a, v130
	v_mul_f32_e32 v130, 0xbfb8aa3b, v130
	v_exp_f32_e32 v130, v130
	s_nop 0
	v_add_f32_e32 v130, 1.0, v130
	v_rcp_f32_e32 v170, v130
	v_mul_f32_e32 v130, 0x3d372713, v129
	v_mul_f32_e32 v130, v129, v130
	v_fma_f32 v130, v129, v130, v129
	v_mul_f32_e32 v130, 0x3fcc422a, v130
	v_mul_f32_e32 v130, 0xbfb8aa3b, v130
	v_exp_f32_e32 v130, v130
	s_nop 0
	v_add_f32_e32 v130, 1.0, v130
	v_rcp_f32_e32 v171, v130
	s_nop 0
	v_pk_mul_f32 v[170:171], v[128:129], v[170:171]
	v_lshlrev_b32_e32 v128, 16, v131
	v_and_b32_e32 v129, 0xffff0000, v131
	v_pk_fma_f32 v[128:129], v[172:173], v[128:129], v[98:99]
	s_nop 0
	v_mul_f32_e32 v130, 0x3d372713, v128
	v_mul_f32_e32 v131, 0x3d372713, v129
	v_mul_f32_e32 v130, v128, v130
	v_mul_f32_e32 v131, v129, v131
	v_fma_f32 v130, v128, v130, v128
	v_fma_f32 v131, v129, v131, v129
	v_mul_f32_e32 v130, 0x3fcc422a, v130
	v_mul_f32_e32 v131, 0x3fcc422a, v131
	v_mul_f32_e32 v130, 0xbfb8aa3b, v130
	v_mul_f32_e32 v131, 0xbfb8aa3b, v131
	v_exp_f32_e32 v130, v130
	v_exp_f32_e32 v131, v131
	v_add_f32_e32 v130, 1.0, v130
	v_add_f32_e32 v131, 1.0, v131
	v_rcp_f32_e32 v130, v130
	v_rcp_f32_e32 v131, v131
	s_nop 0
	v_pk_mul_f32 v[172:173], v[128:129], v[130:131]
	v_cvt_pk_bf16_f32 v128, v138, v139
	v_or_b32_e32 v138, v140, v186
	v_lshlrev_b32_e32 v138, 11, v138
	v_mov_b32_e32 v139, v145
	v_lshl_add_u64 v[138:139], s[90:91], 0, v[138:139]
	v_lshl_add_u64 v[138:139], v[138:139], 0, s[6:7]
	v_cvt_pk_bf16_f32 v129, v142, v143
	v_cvt_pk_bf16_f32 v130, v170, v171
	v_cvt_pk_bf16_f32 v131, v172, v173
	v_lshl_add_u64 v[138:139], v[138:139], 0, v[166:167]
	v_mov_b32_e32 v96, v128
	v_mov_b32_e32 v97, v129
	v_mov_b32_e32 v98, v130
	v_mov_b32_e32 v99, v131
	v_mov_b32_e32 v100, v138
	v_mov_b32_e32 v101, v139
	s_waitcnt vmcnt(1)
	v_mov_b32_e32 v128, v198
	v_mov_b32_e32 v129, v199
	v_mov_b32_e32 v130, v200
	v_mov_b32_e32 v131, v201
	v_add_u32_e32 v214, 0x30, v168
	v_mad_i64_i32 v[212:213], vcc, v214, s69, v[210:211]
	global_load_dwordx4 v[194:197], v[212:213], off offset:256
	v_lshlrev_b32_e32 v142, 16, v128
	v_and_b32_e32 v143, 0xffff0000, v128
	v_mov_b32_e32 v136, v202
	v_mov_b32_e32 v137, v203
	v_mov_b32_e32 v138, v204
	v_mov_b32_e32 v139, v205
	v_mov_b32_e32 v170, v206
	v_mov_b32_e32 v171, v207
	v_mov_b32_e32 v172, v208
	v_mov_b32_e32 v173, v209
	v_pk_fma_f32 v[142:143], v[170:171], v[142:143], v[76:77]
	s_nop 0
	v_mul_f32_e32 v128, 0x3d372713, v142
	v_mul_f32_e32 v128, v142, v128
	v_fma_f32 v128, v142, v128, v142
	v_mul_f32_e32 v128, 0x3fcc422a, v128
	v_mul_f32_e32 v128, 0xbfb8aa3b, v128
	v_exp_f32_e32 v128, v128
	s_nop 0
	v_add_f32_e32 v128, 1.0, v128
	v_rcp_f32_e32 v170, v128
	v_mul_f32_e32 v128, 0x3d372713, v143
	v_mul_f32_e32 v128, v143, v128
	v_fma_f32 v128, v143, v128, v143
	v_mul_f32_e32 v128, 0x3fcc422a, v128
	v_mul_f32_e32 v128, 0xbfb8aa3b, v128
	v_exp_f32_e32 v128, v128
	s_nop 0
	v_add_f32_e32 v128, 1.0, v128
	v_rcp_f32_e32 v171, v128
	v_lshlrev_b32_e32 v128, 16, v129
	v_and_b32_e32 v129, 0xffff0000, v129
	v_pk_fma_f32 v[128:129], v[172:173], v[128:129], v[78:79]
	v_pk_mul_f32 v[142:143], v[142:143], v[170:171]
	v_mul_f32_e32 v141, 0x3d372713, v128
	v_mul_f32_e32 v141, v128, v141
	v_fma_f32 v141, v128, v141, v128
	v_mul_f32_e32 v141, 0x3fcc422a, v141
	v_mul_f32_e32 v141, 0xbfb8aa3b, v141
	v_exp_f32_e32 v141, v141
	s_nop 0
	v_add_f32_e32 v141, 1.0, v141
	v_rcp_f32_e32 v170, v141
	v_mul_f32_e32 v141, 0x3d372713, v129
	v_mul_f32_e32 v141, v129, v141
	v_fma_f32 v141, v129, v141, v129
	v_mul_f32_e32 v141, 0x3fcc422a, v141
	v_mul_f32_e32 v141, 0xbfb8aa3b, v141
	v_exp_f32_e32 v141, v141
	s_nop 0
	v_add_f32_e32 v141, 1.0, v141
	v_rcp_f32_e32 v171, v141
	s_nop 0
	v_pk_mul_f32 v[170:171], v[128:129], v[170:171]
	v_lshlrev_b32_e32 v128, 16, v130
	v_and_b32_e32 v129, 0xffff0000, v130
	v_pk_fma_f32 v[128:129], v[136:137], v[128:129], v[72:73]
	s_nop 0
	v_mul_f32_e32 v130, 0x3d372713, v128
	v_mul_f32_e32 v130, v128, v130
	v_fma_f32 v130, v128, v130, v128
	v_mul_f32_e32 v130, 0x3fcc422a, v130
	v_mul_f32_e32 v130, 0xbfb8aa3b, v130
	v_exp_f32_e32 v130, v130
	s_nop 0
	v_add_f32_e32 v130, 1.0, v130
	v_rcp_f32_e32 v136, v130
	v_mul_f32_e32 v130, 0x3d372713, v129
	v_mul_f32_e32 v130, v129, v130
	v_fma_f32 v130, v129, v130, v129
	v_mul_f32_e32 v130, 0x3fcc422a, v130
	v_mul_f32_e32 v130, 0xbfb8aa3b, v130
	v_exp_f32_e32 v130, v130
	s_nop 0
	v_add_f32_e32 v130, 1.0, v130
	v_rcp_f32_e32 v137, v130
	s_nop 0
	v_pk_mul_f32 v[136:137], v[128:129], v[136:137]
	v_lshlrev_b32_e32 v128, 16, v131
	v_and_b32_e32 v129, 0xffff0000, v131
	v_pk_fma_f32 v[128:129], v[138:139], v[128:129], v[74:75]
	s_nop 0
	v_mul_f32_e32 v130, 0x3d372713, v128
	v_mul_f32_e32 v131, 0x3d372713, v129
	v_mul_f32_e32 v130, v128, v130
	v_mul_f32_e32 v131, v129, v131
	v_fma_f32 v130, v128, v130, v128
	v_fma_f32 v131, v129, v131, v129
	v_mul_f32_e32 v130, 0x3fcc422a, v130
	v_mul_f32_e32 v131, 0x3fcc422a, v131
	v_mul_f32_e32 v130, 0xbfb8aa3b, v130
	v_mul_f32_e32 v131, 0xbfb8aa3b, v131
	v_exp_f32_e32 v130, v130
	v_exp_f32_e32 v131, v131
	v_add_f32_e32 v130, 1.0, v130
	v_add_f32_e32 v131, 1.0, v131
	v_rcp_f32_e32 v130, v130
	v_rcp_f32_e32 v131, v131
	s_nop 0
	v_pk_mul_f32 v[138:139], v[128:129], v[130:131]
	v_cvt_pk_bf16_f32 v130, v136, v137
	v_or_b32_e32 v136, v140, v187
	v_lshlrev_b32_e32 v136, 11, v136
	v_mov_b32_e32 v137, v145
	v_lshl_add_u64 v[136:137], s[90:91], 0, v[136:137]
	v_lshl_add_u64 v[136:137], v[136:137], 0, s[6:7]
	v_cvt_pk_bf16_f32 v128, v142, v143
	v_cvt_pk_bf16_f32 v129, v170, v171
	v_cvt_pk_bf16_f32 v131, v138, v139
	v_lshl_add_u64 v[136:137], v[136:137], 0, v[166:167]
	v_mov_b32_e32 v72, v128
	v_mov_b32_e32 v73, v129
	v_mov_b32_e32 v74, v130
	v_mov_b32_e32 v75, v131
	v_mov_b32_e32 v76, v136
	v_mov_b32_e32 v77, v137
	s_nop 1
	v_or_b32_e32 v130, 48, v168
	v_mad_i64_i32 v[128:129], s[42:43], v130, s69, v[132:133]
	v_lshlrev_b32_e32 v130, 4, v130
	v_lshl_add_u64 v[136:137], v[128:129], 0, v[144:145]
	v_and_b32_e32 v140, 0x3ff0, v130
	s_waitcnt vmcnt(1)
	v_mov_b32_e32 v128, v190
	v_mov_b32_e32 v129, v191
	v_mov_b32_e32 v130, v192
	v_mov_b32_e32 v131, v193
	v_add_u32_e32 v214, 0x80, v168
	v_mad_i64_i32 v[212:213], vcc, v214, s69, v[210:211]
	global_load_dwordx4 v[198:201], v[212:213], off
	v_lshlrev_b32_e32 v138, 16, v128
	v_and_b32_e32 v139, 0xffff0000, v128
	v_mov_b32_e32 v170, v202
	v_mov_b32_e32 v171, v203
	v_mov_b32_e32 v172, v204
	v_mov_b32_e32 v173, v205
	v_mov_b32_e32 v174, v206
	v_mov_b32_e32 v175, v207
	v_mov_b32_e32 v176, v208
	v_mov_b32_e32 v177, v209
	v_pk_fma_f32 v[138:139], v[174:175], v[138:139], v[84:85]
	s_nop 0
	v_mul_f32_e32 v128, 0x3d372713, v138
	v_mul_f32_e32 v128, v138, v128
	v_fma_f32 v128, v138, v128, v138
	v_mul_f32_e32 v128, 0x3fcc422a, v128
	v_mul_f32_e32 v128, 0xbfb8aa3b, v128
	v_exp_f32_e32 v128, v128
	s_nop 0
	v_add_f32_e32 v128, 1.0, v128
	v_rcp_f32_e32 v142, v128
	v_mul_f32_e32 v128, 0x3d372713, v139
	v_mul_f32_e32 v128, v139, v128
	v_fma_f32 v128, v139, v128, v139
	v_mul_f32_e32 v128, 0x3fcc422a, v128
	v_mul_f32_e32 v128, 0xbfb8aa3b, v128
	v_exp_f32_e32 v128, v128
	s_nop 0
	v_add_f32_e32 v128, 1.0, v128
	v_rcp_f32_e32 v143, v128
	v_lshlrev_b32_e32 v128, 16, v129
	v_and_b32_e32 v129, 0xffff0000, v129
	v_pk_fma_f32 v[128:129], v[176:177], v[128:129], v[86:87]
	v_pk_mul_f32 v[138:139], v[138:139], v[142:143]
	v_mul_f32_e32 v141, 0x3d372713, v128
	v_mul_f32_e32 v141, v128, v141
	v_fma_f32 v141, v128, v141, v128
	v_mul_f32_e32 v141, 0x3fcc422a, v141
	v_mul_f32_e32 v141, 0xbfb8aa3b, v141
	v_exp_f32_e32 v141, v141
	s_nop 0
	v_add_f32_e32 v141, 1.0, v141
	v_rcp_f32_e32 v142, v141
	v_mul_f32_e32 v141, 0x3d372713, v129
	v_mul_f32_e32 v141, v129, v141
	v_fma_f32 v141, v129, v141, v129
	v_mul_f32_e32 v141, 0x3fcc422a, v141
	v_mul_f32_e32 v141, 0xbfb8aa3b, v141
	v_exp_f32_e32 v141, v141
	s_nop 0
	v_add_f32_e32 v141, 1.0, v141
	v_rcp_f32_e32 v143, v141
	s_nop 0
	v_pk_mul_f32 v[142:143], v[128:129], v[142:143]
	v_lshlrev_b32_e32 v128, 16, v130
	v_and_b32_e32 v129, 0xffff0000, v130
	v_pk_fma_f32 v[128:129], v[170:171], v[128:129], v[80:81]
	s_nop 0
	v_mul_f32_e32 v130, 0x3d372713, v128
	v_mul_f32_e32 v130, v128, v130
	v_fma_f32 v130, v128, v130, v128
	v_mul_f32_e32 v130, 0x3fcc422a, v130
	v_mul_f32_e32 v130, 0xbfb8aa3b, v130
	v_exp_f32_e32 v130, v130
	s_nop 0
	v_add_f32_e32 v130, 1.0, v130
	v_rcp_f32_e32 v170, v130
	v_mul_f32_e32 v130, 0x3d372713, v129
	v_mul_f32_e32 v130, v129, v130
	v_fma_f32 v130, v129, v130, v129
	v_mul_f32_e32 v130, 0x3fcc422a, v130
	v_mul_f32_e32 v130, 0xbfb8aa3b, v130
	v_exp_f32_e32 v130, v130
	s_nop 0
	v_add_f32_e32 v130, 1.0, v130
	v_rcp_f32_e32 v171, v130
	s_nop 0
	v_pk_mul_f32 v[170:171], v[128:129], v[170:171]
	v_lshlrev_b32_e32 v128, 16, v131
	v_and_b32_e32 v129, 0xffff0000, v131
	v_pk_fma_f32 v[128:129], v[172:173], v[128:129], v[82:83]
	s_nop 0
	v_mul_f32_e32 v130, 0x3d372713, v128
	v_mul_f32_e32 v131, 0x3d372713, v129
	v_mul_f32_e32 v130, v128, v130
	v_mul_f32_e32 v131, v129, v131
	v_fma_f32 v130, v128, v130, v128
	v_fma_f32 v131, v129, v131, v129
	v_mul_f32_e32 v130, 0x3fcc422a, v130
	v_mul_f32_e32 v131, 0x3fcc422a, v131
	v_mul_f32_e32 v130, 0xbfb8aa3b, v130
	v_mul_f32_e32 v131, 0xbfb8aa3b, v131
	v_exp_f32_e32 v130, v130
	v_exp_f32_e32 v131, v131
	v_add_f32_e32 v130, 1.0, v130
	v_add_f32_e32 v131, 1.0, v131
	v_rcp_f32_e32 v130, v130
	v_rcp_f32_e32 v131, v131
	s_nop 0
	v_pk_mul_f32 v[172:173], v[128:129], v[130:131]
	v_cvt_pk_bf16_f32 v128, v138, v139
	v_or_b32_e32 v138, v140, v186
	v_lshlrev_b32_e32 v138, 11, v138
	v_mov_b32_e32 v139, v145
	v_lshl_add_u64 v[138:139], s[90:91], 0, v[138:139]
	v_lshl_add_u64 v[138:139], v[138:139], 0, s[6:7]
	v_cvt_pk_bf16_f32 v129, v142, v143
	v_cvt_pk_bf16_f32 v130, v170, v171
	v_cvt_pk_bf16_f32 v131, v172, v173
	v_lshl_add_u64 v[138:139], v[138:139], 0, v[166:167]
	v_mov_b32_e32 v80, v128
	v_mov_b32_e32 v81, v129
	v_mov_b32_e32 v82, v130
	v_mov_b32_e32 v83, v131
	v_mov_b32_e32 v84, v138
	v_mov_b32_e32 v85, v139
	s_waitcnt vmcnt(1)
	v_mov_b32_e32 v128, v194
	v_mov_b32_e32 v129, v195
	v_mov_b32_e32 v130, v196
	v_mov_b32_e32 v131, v197
	v_add_u32_e32 v214, 0x80, v168
	v_mad_i64_i32 v[212:213], vcc, v214, s69, v[210:211]
	global_load_dwordx4 v[190:193], v[212:213], off offset:256
	v_lshlrev_b32_e32 v134, 16, v128
	v_and_b32_e32 v135, 0xffff0000, v128
	v_mov_b32_e32 v136, v202
	v_mov_b32_e32 v137, v203
	v_mov_b32_e32 v138, v204
	v_mov_b32_e32 v139, v205
	v_mov_b32_e32 v170, v206
	v_mov_b32_e32 v171, v207
	v_mov_b32_e32 v172, v208
	v_mov_b32_e32 v173, v209
	v_pk_fma_f32 v[134:135], v[170:171], v[134:135], v[68:69]
	s_nop 0
	v_mul_f32_e32 v128, 0x3d372713, v134
	v_mul_f32_e32 v128, v134, v128
	v_fma_f32 v128, v134, v128, v134
	v_mul_f32_e32 v128, 0x3fcc422a, v128
	v_mul_f32_e32 v128, 0xbfb8aa3b, v128
	v_exp_f32_e32 v128, v128
	s_nop 0
	v_add_f32_e32 v128, 1.0, v128
	v_rcp_f32_e32 v142, v128
	v_mul_f32_e32 v128, 0x3d372713, v135
	v_mul_f32_e32 v128, v135, v128
	v_fma_f32 v128, v135, v128, v135
	v_mul_f32_e32 v128, 0x3fcc422a, v128
	v_mul_f32_e32 v128, 0xbfb8aa3b, v128
	v_exp_f32_e32 v128, v128
	s_nop 0
	v_add_f32_e32 v128, 1.0, v128
	v_rcp_f32_e32 v143, v128
	v_lshlrev_b32_e32 v128, 16, v129
	v_and_b32_e32 v129, 0xffff0000, v129
	v_pk_fma_f32 v[128:129], v[172:173], v[128:129], v[70:71]
	v_pk_mul_f32 v[134:135], v[134:135], v[142:143]
	v_mul_f32_e32 v141, 0x3d372713, v128
	v_mul_f32_e32 v141, v128, v141
	v_fma_f32 v141, v128, v141, v128
	v_mul_f32_e32 v141, 0x3fcc422a, v141
	v_mul_f32_e32 v141, 0xbfb8aa3b, v141
	v_exp_f32_e32 v141, v141
	s_nop 0
	v_add_f32_e32 v141, 1.0, v141
	v_rcp_f32_e32 v142, v141
	v_mul_f32_e32 v141, 0x3d372713, v129
	v_mul_f32_e32 v141, v129, v141
	v_fma_f32 v141, v129, v141, v129
	v_mul_f32_e32 v141, 0x3fcc422a, v141
	v_mul_f32_e32 v141, 0xbfb8aa3b, v141
	v_exp_f32_e32 v141, v141
	s_nop 0
	v_add_f32_e32 v141, 1.0, v141
	v_rcp_f32_e32 v143, v141
	s_nop 0
	v_pk_mul_f32 v[142:143], v[128:129], v[142:143]
	v_lshlrev_b32_e32 v128, 16, v130
	v_and_b32_e32 v129, 0xffff0000, v130
	v_pk_fma_f32 v[128:129], v[136:137], v[128:129], v[64:65]
	s_nop 0
	v_mul_f32_e32 v130, 0x3d372713, v128
	v_mul_f32_e32 v130, v128, v130
	v_fma_f32 v130, v128, v130, v128
	v_mul_f32_e32 v130, 0x3fcc422a, v130
	v_mul_f32_e32 v130, 0xbfb8aa3b, v130
	v_exp_f32_e32 v130, v130
	s_nop 0
	v_add_f32_e32 v130, 1.0, v130
	v_rcp_f32_e32 v136, v130
	v_mul_f32_e32 v130, 0x3d372713, v129
	v_mul_f32_e32 v130, v129, v130
	v_fma_f32 v130, v129, v130, v129
	v_mul_f32_e32 v130, 0x3fcc422a, v130
	v_mul_f32_e32 v130, 0xbfb8aa3b, v130
	v_exp_f32_e32 v130, v130
	s_nop 0
	v_add_f32_e32 v130, 1.0, v130
	v_rcp_f32_e32 v137, v130
	s_nop 0
	v_pk_mul_f32 v[136:137], v[128:129], v[136:137]
	v_lshlrev_b32_e32 v128, 16, v131
	v_and_b32_e32 v129, 0xffff0000, v131
	v_pk_fma_f32 v[128:129], v[138:139], v[128:129], v[66:67]
	s_nop 0
	v_mul_f32_e32 v130, 0x3d372713, v128
	v_mul_f32_e32 v131, 0x3d372713, v129
	v_mul_f32_e32 v130, v128, v130
	v_mul_f32_e32 v131, v129, v131
	v_fma_f32 v130, v128, v130, v128
	v_fma_f32 v131, v129, v131, v129
	v_mul_f32_e32 v130, 0x3fcc422a, v130
	v_mul_f32_e32 v131, 0x3fcc422a, v131
	v_mul_f32_e32 v130, 0xbfb8aa3b, v130
	v_mul_f32_e32 v131, 0xbfb8aa3b, v131
	v_exp_f32_e32 v130, v130
	v_exp_f32_e32 v131, v131
	v_add_f32_e32 v130, 1.0, v130
	v_add_f32_e32 v131, 1.0, v131
	v_rcp_f32_e32 v130, v130
	v_rcp_f32_e32 v131, v131
	s_nop 0
	v_pk_mul_f32 v[138:139], v[128:129], v[130:131]
	v_cvt_pk_bf16_f32 v128, v134, v135
	v_or_b32_e32 v134, v140, v187
	v_lshlrev_b32_e32 v134, 11, v134
	v_mov_b32_e32 v135, v145
	v_lshl_add_u64 v[134:135], s[90:91], 0, v[134:135]
	v_lshl_add_u64 v[134:135], v[134:135], 0, s[6:7]
	v_cvt_pk_bf16_f32 v129, v142, v143
	v_cvt_pk_bf16_f32 v130, v136, v137
	v_cvt_pk_bf16_f32 v131, v138, v139
	v_lshl_add_u64 v[134:135], v[134:135], 0, v[166:167]
	v_mov_b32_e32 v64, v128
	v_mov_b32_e32 v65, v129
	v_mov_b32_e32 v66, v130
	v_mov_b32_e32 v67, v131
	v_mov_b32_e32 v68, v134
	v_mov_b32_e32 v69, v135
	s_nop 1
	v_add_u32_e32 v130, 0x80, v168
	v_ashrrev_i32_e32 v128, 6, v130
	v_and_b32_e32 v136, -16, v128
	v_mad_i64_i32 v[128:129], s[6:7], v130, s69, v[132:133]
	v_ashrrev_i32_e32 v137, 31, v136
	v_lshlrev_b32_e32 v130, 4, v130
	v_lshl_add_u64 v[138:139], v[128:129], 0, v[144:145]
	v_lshl_add_u64 v[134:135], v[136:137], 2, v[160:161]
	v_and_b32_e32 v142, 0x3cf0, v130
	v_lshlrev_b64 v[136:137], 1, v[136:137]
	s_waitcnt vmcnt(1)
	v_mov_b32_e32 v128, v198
	v_mov_b32_e32 v129, v199
	v_mov_b32_e32 v130, v200
	v_mov_b32_e32 v131, v201
	v_add_u32_e32 v214, 0x90, v168
	v_mad_i64_i32 v[212:213], vcc, v214, s69, v[210:211]
	global_load_dwordx4 v[194:197], v[212:213], off
	v_lshlrev_b32_e32 v140, 16, v128
	v_and_b32_e32 v141, 0xffff0000, v128
	v_mov_b32_e32 v170, v202
	v_mov_b32_e32 v171, v203
	v_mov_b32_e32 v172, v204
	v_mov_b32_e32 v173, v205
	v_mov_b32_e32 v174, v206
	v_mov_b32_e32 v175, v207
	v_mov_b32_e32 v176, v208
	v_mov_b32_e32 v177, v209
	v_pk_fma_f32 v[140:141], v[174:175], v[140:141], v[60:61]
	s_nop 0
	v_mul_f32_e32 v128, 0x3d372713, v140
	v_mul_f32_e32 v128, v140, v128
	v_fma_f32 v128, v140, v128, v140
	v_mul_f32_e32 v128, 0x3fcc422a, v128
	v_mul_f32_e32 v128, 0xbfb8aa3b, v128
	v_exp_f32_e32 v128, v128
	s_nop 0
	v_add_f32_e32 v128, 1.0, v128
	v_rcp_f32_e32 v174, v128
	v_mul_f32_e32 v128, 0x3d372713, v141
	v_mul_f32_e32 v128, v141, v128
	v_fma_f32 v128, v141, v128, v141
	v_mul_f32_e32 v128, 0x3fcc422a, v128
	v_mul_f32_e32 v128, 0xbfb8aa3b, v128
	v_exp_f32_e32 v128, v128
	s_nop 0
	v_add_f32_e32 v128, 1.0, v128
	v_rcp_f32_e32 v175, v128
	v_lshlrev_b32_e32 v128, 16, v129
	v_and_b32_e32 v129, 0xffff0000, v129
	v_pk_fma_f32 v[128:129], v[176:177], v[128:129], v[62:63]
	v_pk_mul_f32 v[140:141], v[140:141], v[174:175]
	v_mul_f32_e32 v143, 0x3d372713, v128
	v_mul_f32_e32 v143, v128, v143
	v_fma_f32 v143, v128, v143, v128
	v_mul_f32_e32 v143, 0x3fcc422a, v143
	v_mul_f32_e32 v143, 0xbfb8aa3b, v143
	v_exp_f32_e32 v143, v143
	s_nop 0
	v_add_f32_e32 v143, 1.0, v143
	v_rcp_f32_e32 v174, v143
	v_mul_f32_e32 v143, 0x3d372713, v129
	v_mul_f32_e32 v143, v129, v143
	v_fma_f32 v143, v129, v143, v129
	v_mul_f32_e32 v143, 0x3fcc422a, v143
	v_mul_f32_e32 v143, 0xbfb8aa3b, v143
	v_exp_f32_e32 v143, v143
	s_nop 0
	v_add_f32_e32 v143, 1.0, v143
	v_rcp_f32_e32 v175, v143
	s_nop 0
	v_pk_mul_f32 v[174:175], v[128:129], v[174:175]
	v_lshlrev_b32_e32 v128, 16, v130
	v_and_b32_e32 v129, 0xffff0000, v130
	v_pk_fma_f32 v[128:129], v[170:171], v[128:129], v[56:57]
	s_nop 0
	v_mul_f32_e32 v130, 0x3d372713, v128
	v_mul_f32_e32 v130, v128, v130
	v_fma_f32 v130, v128, v130, v128
	v_mul_f32_e32 v130, 0x3fcc422a, v130
	v_mul_f32_e32 v130, 0xbfb8aa3b, v130
	v_exp_f32_e32 v130, v130
	s_nop 0
	v_add_f32_e32 v130, 1.0, v130
	v_rcp_f32_e32 v170, v130
	v_mul_f32_e32 v130, 0x3d372713, v129
	v_mul_f32_e32 v130, v129, v130
	v_fma_f32 v130, v129, v130, v129
	v_mul_f32_e32 v130, 0x3fcc422a, v130
	v_mul_f32_e32 v130, 0xbfb8aa3b, v130
	v_exp_f32_e32 v130, v130
	s_nop 0
	v_add_f32_e32 v130, 1.0, v130
	v_rcp_f32_e32 v171, v130
	s_nop 0
	v_pk_mul_f32 v[170:171], v[128:129], v[170:171]
	v_lshlrev_b32_e32 v128, 16, v131
	v_and_b32_e32 v129, 0xffff0000, v131
	v_pk_fma_f32 v[128:129], v[172:173], v[128:129], v[58:59]
	s_nop 0
	v_mul_f32_e32 v130, 0x3d372713, v128
	v_mul_f32_e32 v131, 0x3d372713, v129
	v_mul_f32_e32 v130, v128, v130
	v_mul_f32_e32 v131, v129, v131
	v_fma_f32 v130, v128, v130, v128
	v_fma_f32 v131, v129, v131, v129
	v_mul_f32_e32 v130, 0x3fcc422a, v130
	v_mul_f32_e32 v131, 0x3fcc422a, v131
	v_mul_f32_e32 v130, 0xbfb8aa3b, v130
	v_mul_f32_e32 v131, 0xbfb8aa3b, v131
	v_exp_f32_e32 v130, v130
	v_exp_f32_e32 v131, v131
	v_add_f32_e32 v130, 1.0, v130
	v_add_f32_e32 v131, 1.0, v131
	v_rcp_f32_e32 v130, v130
	v_rcp_f32_e32 v131, v131
	s_nop 0
	v_pk_mul_f32 v[172:173], v[128:129], v[130:131]
	v_cvt_pk_bf16_f32 v128, v140, v141
	v_or_b32_e32 v140, v142, v186
	v_lshlrev_b32_e32 v140, 11, v140
	v_mov_b32_e32 v141, v145
	v_lshl_add_u64 v[140:141], s[90:91], 0, v[140:141]
	v_lshl_add_u64 v[140:141], v[140:141], 0, v[136:137]
	v_cvt_pk_bf16_f32 v129, v174, v175
	v_cvt_pk_bf16_f32 v130, v170, v171
	v_cvt_pk_bf16_f32 v131, v172, v173
	v_lshl_add_u64 v[140:141], v[140:141], 0, v[166:167]
	v_mov_b32_e32 v56, v128
	v_mov_b32_e32 v57, v129
	v_mov_b32_e32 v58, v130
	v_mov_b32_e32 v59, v131
	v_mov_b32_e32 v60, v140
	v_mov_b32_e32 v61, v141
	s_waitcnt vmcnt(1)
	v_mov_b32_e32 v128, v190
	v_mov_b32_e32 v129, v191
	v_mov_b32_e32 v130, v192
	v_mov_b32_e32 v131, v193
	v_add_u32_e32 v214, 0x90, v168
	v_mad_i64_i32 v[212:213], vcc, v214, s69, v[210:211]
	global_load_dwordx4 v[198:201], v[212:213], off offset:256
	v_lshlrev_b32_e32 v174, 16, v128
	v_and_b32_e32 v175, 0xffff0000, v128
	v_mov_b32_e32 v138, v202
	v_mov_b32_e32 v139, v203
	v_mov_b32_e32 v140, v204
	v_mov_b32_e32 v141, v205
	v_mov_b32_e32 v170, v206
	v_mov_b32_e32 v171, v207
	v_mov_b32_e32 v172, v208
	v_mov_b32_e32 v173, v209
	v_pk_fma_f32 v[170:171], v[170:171], v[174:175], v[44:45]
	s_nop 0
	v_mul_f32_e32 v128, 0x3d372713, v170
	v_mul_f32_e32 v128, v170, v128
	v_fma_f32 v128, v170, v128, v170
	v_mul_f32_e32 v128, 0x3fcc422a, v128
	v_mul_f32_e32 v128, 0xbfb8aa3b, v128
	v_exp_f32_e32 v128, v128
	s_nop 0
	v_add_f32_e32 v128, 1.0, v128
	v_rcp_f32_e32 v174, v128
	v_mul_f32_e32 v128, 0x3d372713, v171
	v_mul_f32_e32 v128, v171, v128
	v_fma_f32 v128, v171, v128, v171
	v_mul_f32_e32 v128, 0x3fcc422a, v128
	v_mul_f32_e32 v128, 0xbfb8aa3b, v128
	v_exp_f32_e32 v128, v128
	s_nop 0
	v_add_f32_e32 v128, 1.0, v128
	v_rcp_f32_e32 v175, v128
	v_lshlrev_b32_e32 v128, 16, v129
	v_and_b32_e32 v129, 0xffff0000, v129
	v_pk_fma_f32 v[128:129], v[172:173], v[128:129], v[46:47]
	v_pk_mul_f32 v[170:171], v[170:171], v[174:175]
	v_mul_f32_e32 v143, 0x3d372713, v128
	v_mul_f32_e32 v143, v128, v143
	v_fma_f32 v143, v128, v143, v128
	v_mul_f32_e32 v143, 0x3fcc422a, v143
	v_mul_f32_e32 v143, 0xbfb8aa3b, v143
	v_exp_f32_e32 v143, v143
	s_nop 0
	v_add_f32_e32 v143, 1.0, v143
	v_rcp_f32_e32 v172, v143
	v_mul_f32_e32 v143, 0x3d372713, v129
	v_mul_f32_e32 v143, v129, v143
	v_fma_f32 v143, v129, v143, v129
	v_mul_f32_e32 v143, 0x3fcc422a, v143
	v_mul_f32_e32 v143, 0xbfb8aa3b, v143
	v_exp_f32_e32 v143, v143
	s_nop 0
	v_add_f32_e32 v143, 1.0, v143
	v_rcp_f32_e32 v173, v143
	s_nop 0
	v_pk_mul_f32 v[172:173], v[128:129], v[172:173]
	v_lshlrev_b32_e32 v128, 16, v130
	v_and_b32_e32 v129, 0xffff0000, v130
	v_pk_fma_f32 v[128:129], v[138:139], v[128:129], v[40:41]
	s_nop 0
	v_mul_f32_e32 v130, 0x3d372713, v128
	v_mul_f32_e32 v130, v128, v130
	v_fma_f32 v130, v128, v130, v128
	v_mul_f32_e32 v130, 0x3fcc422a, v130
	v_mul_f32_e32 v130, 0xbfb8aa3b, v130
	v_exp_f32_e32 v130, v130
	s_nop 0
	v_add_f32_e32 v130, 1.0, v130
	v_rcp_f32_e32 v138, v130
	v_mul_f32_e32 v130, 0x3d372713, v129
	v_mul_f32_e32 v130, v129, v130
	v_fma_f32 v130, v129, v130, v129
	v_mul_f32_e32 v130, 0x3fcc422a, v130
	v_mul_f32_e32 v130, 0xbfb8aa3b, v130
	v_exp_f32_e32 v130, v130
	s_nop 0
	v_add_f32_e32 v130, 1.0, v130
	v_rcp_f32_e32 v139, v130
	s_nop 0
	v_pk_mul_f32 v[138:139], v[128:129], v[138:139]
	v_lshlrev_b32_e32 v128, 16, v131
	v_and_b32_e32 v129, 0xffff0000, v131
	v_pk_fma_f32 v[128:129], v[140:141], v[128:129], v[42:43]
	s_nop 0
	v_mul_f32_e32 v130, 0x3d372713, v128
	v_mul_f32_e32 v131, 0x3d372713, v129
	v_mul_f32_e32 v130, v128, v130
	v_mul_f32_e32 v131, v129, v131
	v_fma_f32 v130, v128, v130, v128
	v_fma_f32 v131, v129, v131, v129
	v_mul_f32_e32 v130, 0x3fcc422a, v130
	v_mul_f32_e32 v131, 0x3fcc422a, v131
	v_mul_f32_e32 v130, 0xbfb8aa3b, v130
	v_mul_f32_e32 v131, 0xbfb8aa3b, v131
	v_exp_f32_e32 v130, v130
	v_exp_f32_e32 v131, v131
	v_add_f32_e32 v130, 1.0, v130
	v_add_f32_e32 v131, 1.0, v131
	v_rcp_f32_e32 v130, v130
	v_rcp_f32_e32 v131, v131
	s_nop 0
	v_pk_mul_f32 v[140:141], v[128:129], v[130:131]
	v_cvt_pk_bf16_f32 v130, v138, v139
	v_or_b32_e32 v138, v142, v187
	v_lshlrev_b32_e32 v138, 11, v138
	v_mov_b32_e32 v139, v145
	v_lshl_add_u64 v[138:139], s[90:91], 0, v[138:139]
	v_lshl_add_u64 v[138:139], v[138:139], 0, v[136:137]
	v_cvt_pk_bf16_f32 v128, v170, v171
	v_cvt_pk_bf16_f32 v129, v172, v173
	v_cvt_pk_bf16_f32 v131, v140, v141
	v_lshl_add_u64 v[138:139], v[138:139], 0, v[166:167]
	v_mov_b32_e32 v40, v128
	v_mov_b32_e32 v41, v129
	v_mov_b32_e32 v42, v130
	v_mov_b32_e32 v43, v131
	v_mov_b32_e32 v44, v138
	v_mov_b32_e32 v45, v139
	s_nop 1
	v_add_u32_e32 v130, 0x90, v168
	v_mad_i64_i32 v[128:129], s[6:7], v130, s69, v[132:133]
	v_lshlrev_b32_e32 v130, 4, v130
	v_lshl_add_u64 v[138:139], v[128:129], 0, v[144:145]
	v_and_b32_e32 v142, 0x3df0, v130
	s_waitcnt vmcnt(1)
	v_mov_b32_e32 v128, v194
	v_mov_b32_e32 v129, v195
	v_mov_b32_e32 v130, v196
	v_mov_b32_e32 v131, v197
	v_add_u32_e32 v214, 0xa0, v168
	v_mad_i64_i32 v[212:213], vcc, v214, s69, v[210:211]
	global_load_dwordx4 v[190:193], v[212:213], off
	v_lshlrev_b32_e32 v140, 16, v128
	v_and_b32_e32 v141, 0xffff0000, v128
	v_mov_b32_e32 v170, v202
	v_mov_b32_e32 v171, v203
	v_mov_b32_e32 v172, v204
	v_mov_b32_e32 v173, v205
	v_mov_b32_e32 v174, v206
	v_mov_b32_e32 v175, v207
	v_mov_b32_e32 v176, v208
	v_mov_b32_e32 v177, v209
	v_pk_fma_f32 v[140:141], v[174:175], v[140:141], v[52:53]
	s_nop 0
	v_mul_f32_e32 v128, 0x3d372713, v140
	v_mul_f32_e32 v128, v140, v128
	v_fma_f32 v128, v140, v128, v140
	v_mul_f32_e32 v128, 0x3fcc422a, v128
	v_mul_f32_e32 v128, 0xbfb8aa3b, v128
	v_exp_f32_e32 v128, v128
	s_nop 0
	v_add_f32_e32 v128, 1.0, v128
	v_rcp_f32_e32 v174, v128
	v_mul_f32_e32 v128, 0x3d372713, v141
	v_mul_f32_e32 v128, v141, v128
	v_fma_f32 v128, v141, v128, v141
	v_mul_f32_e32 v128, 0x3fcc422a, v128
	v_mul_f32_e32 v128, 0xbfb8aa3b, v128
	v_exp_f32_e32 v128, v128
	s_nop 0
	v_add_f32_e32 v128, 1.0, v128
	v_rcp_f32_e32 v175, v128
	v_lshlrev_b32_e32 v128, 16, v129
	v_and_b32_e32 v129, 0xffff0000, v129
	v_pk_fma_f32 v[128:129], v[176:177], v[128:129], v[54:55]
	v_pk_mul_f32 v[140:141], v[140:141], v[174:175]
	v_mul_f32_e32 v143, 0x3d372713, v128
	v_mul_f32_e32 v143, v128, v143
	v_fma_f32 v143, v128, v143, v128
	v_mul_f32_e32 v143, 0x3fcc422a, v143
	v_mul_f32_e32 v143, 0xbfb8aa3b, v143
	v_exp_f32_e32 v143, v143
	s_nop 0
	v_add_f32_e32 v143, 1.0, v143
	v_rcp_f32_e32 v174, v143
	v_mul_f32_e32 v143, 0x3d372713, v129
	v_mul_f32_e32 v143, v129, v143
	v_fma_f32 v143, v129, v143, v129
	v_mul_f32_e32 v143, 0x3fcc422a, v143
	v_mul_f32_e32 v143, 0xbfb8aa3b, v143
	v_exp_f32_e32 v143, v143
	s_nop 0
	v_add_f32_e32 v143, 1.0, v143
	v_rcp_f32_e32 v175, v143
	s_nop 0
	v_pk_mul_f32 v[174:175], v[128:129], v[174:175]
	v_lshlrev_b32_e32 v128, 16, v130
	v_and_b32_e32 v129, 0xffff0000, v130
	v_pk_fma_f32 v[128:129], v[170:171], v[128:129], v[48:49]
	s_nop 0
	v_mul_f32_e32 v130, 0x3d372713, v128
	v_mul_f32_e32 v130, v128, v130
	v_fma_f32 v130, v128, v130, v128
	v_mul_f32_e32 v130, 0x3fcc422a, v130
	v_mul_f32_e32 v130, 0xbfb8aa3b, v130
	v_exp_f32_e32 v130, v130
	s_nop 0
	v_add_f32_e32 v130, 1.0, v130
	v_rcp_f32_e32 v170, v130
	v_mul_f32_e32 v130, 0x3d372713, v129
	v_mul_f32_e32 v130, v129, v130
	v_fma_f32 v130, v129, v130, v129
	v_mul_f32_e32 v130, 0x3fcc422a, v130
	v_mul_f32_e32 v130, 0xbfb8aa3b, v130
	v_exp_f32_e32 v130, v130
	s_nop 0
	v_add_f32_e32 v130, 1.0, v130
	v_rcp_f32_e32 v171, v130
	s_nop 0
	v_pk_mul_f32 v[170:171], v[128:129], v[170:171]
	v_lshlrev_b32_e32 v128, 16, v131
	v_and_b32_e32 v129, 0xffff0000, v131
	v_pk_fma_f32 v[128:129], v[172:173], v[128:129], v[50:51]
	s_nop 0
	v_mul_f32_e32 v130, 0x3d372713, v128
	v_mul_f32_e32 v131, 0x3d372713, v129
	v_mul_f32_e32 v130, v128, v130
	v_mul_f32_e32 v131, v129, v131
	v_fma_f32 v130, v128, v130, v128
	v_fma_f32 v131, v129, v131, v129
	v_mul_f32_e32 v130, 0x3fcc422a, v130
	v_mul_f32_e32 v131, 0x3fcc422a, v131
	v_mul_f32_e32 v130, 0xbfb8aa3b, v130
	v_mul_f32_e32 v131, 0xbfb8aa3b, v131
	v_exp_f32_e32 v130, v130
	v_exp_f32_e32 v131, v131
	v_add_f32_e32 v130, 1.0, v130
	v_add_f32_e32 v131, 1.0, v131
	v_rcp_f32_e32 v130, v130
	v_rcp_f32_e32 v131, v131
	s_nop 0
	v_pk_mul_f32 v[172:173], v[128:129], v[130:131]
	v_cvt_pk_bf16_f32 v128, v140, v141
	v_or_b32_e32 v140, v142, v186
	v_lshlrev_b32_e32 v140, 11, v140
	v_mov_b32_e32 v141, v145
	v_lshl_add_u64 v[140:141], s[90:91], 0, v[140:141]
	v_lshl_add_u64 v[140:141], v[140:141], 0, v[136:137]
	v_cvt_pk_bf16_f32 v129, v174, v175
	v_cvt_pk_bf16_f32 v130, v170, v171
	v_cvt_pk_bf16_f32 v131, v172, v173
	v_lshl_add_u64 v[140:141], v[140:141], 0, v[166:167]
	v_mov_b32_e32 v48, v128
	v_mov_b32_e32 v49, v129
	v_mov_b32_e32 v50, v130
	v_mov_b32_e32 v51, v131
	v_mov_b32_e32 v52, v140
	v_mov_b32_e32 v53, v141
	s_waitcnt vmcnt(1)
	v_mov_b32_e32 v128, v198
	v_mov_b32_e32 v129, v199
	v_mov_b32_e32 v130, v200
	v_mov_b32_e32 v131, v201
	v_add_u32_e32 v214, 0xa0, v168
	v_mad_i64_i32 v[212:213], vcc, v214, s69, v[210:211]
	global_load_dwordx4 v[194:197], v[212:213], off offset:256
	v_lshlrev_b32_e32 v174, 16, v128
	v_and_b32_e32 v175, 0xffff0000, v128
	v_mov_b32_e32 v138, v202
	v_mov_b32_e32 v139, v203
	v_mov_b32_e32 v140, v204
	v_mov_b32_e32 v141, v205
	v_mov_b32_e32 v170, v206
	v_mov_b32_e32 v171, v207
	v_mov_b32_e32 v172, v208
	v_mov_b32_e32 v173, v209
	v_pk_fma_f32 v[170:171], v[170:171], v[174:175], v[28:29]
	s_nop 0
	v_mul_f32_e32 v128, 0x3d372713, v170
	v_mul_f32_e32 v128, v170, v128
	v_fma_f32 v128, v170, v128, v170
	v_mul_f32_e32 v128, 0x3fcc422a, v128
	v_mul_f32_e32 v128, 0xbfb8aa3b, v128
	v_exp_f32_e32 v128, v128
	s_nop 0
	v_add_f32_e32 v128, 1.0, v128
	v_rcp_f32_e32 v174, v128
	v_mul_f32_e32 v128, 0x3d372713, v171
	v_mul_f32_e32 v128, v171, v128
	v_fma_f32 v128, v171, v128, v171
	v_mul_f32_e32 v128, 0x3fcc422a, v128
	v_mul_f32_e32 v128, 0xbfb8aa3b, v128
	v_exp_f32_e32 v128, v128
	s_nop 0
	v_add_f32_e32 v128, 1.0, v128
	v_rcp_f32_e32 v175, v128
	v_lshlrev_b32_e32 v128, 16, v129
	v_and_b32_e32 v129, 0xffff0000, v129
	v_pk_fma_f32 v[128:129], v[172:173], v[128:129], v[30:31]
	v_pk_mul_f32 v[170:171], v[170:171], v[174:175]
	v_mul_f32_e32 v143, 0x3d372713, v128
	v_mul_f32_e32 v143, v128, v143
	v_fma_f32 v143, v128, v143, v128
	v_mul_f32_e32 v143, 0x3fcc422a, v143
	v_mul_f32_e32 v143, 0xbfb8aa3b, v143
	v_exp_f32_e32 v143, v143
	s_nop 0
	v_add_f32_e32 v143, 1.0, v143
	v_rcp_f32_e32 v172, v143
	v_mul_f32_e32 v143, 0x3d372713, v129
	v_mul_f32_e32 v143, v129, v143
	v_fma_f32 v143, v129, v143, v129
	v_mul_f32_e32 v143, 0x3fcc422a, v143
	v_mul_f32_e32 v143, 0xbfb8aa3b, v143
	v_exp_f32_e32 v143, v143
	s_nop 0
	v_add_f32_e32 v143, 1.0, v143
	v_rcp_f32_e32 v173, v143
	s_nop 0
	v_pk_mul_f32 v[172:173], v[128:129], v[172:173]
	v_lshlrev_b32_e32 v128, 16, v130
	v_and_b32_e32 v129, 0xffff0000, v130
	v_pk_fma_f32 v[128:129], v[138:139], v[128:129], v[24:25]
	s_nop 0
	v_mul_f32_e32 v130, 0x3d372713, v128
	v_mul_f32_e32 v130, v128, v130
	v_fma_f32 v130, v128, v130, v128
	v_mul_f32_e32 v130, 0x3fcc422a, v130
	v_mul_f32_e32 v130, 0xbfb8aa3b, v130
	v_exp_f32_e32 v130, v130
	s_nop 0
	v_add_f32_e32 v130, 1.0, v130
	v_rcp_f32_e32 v138, v130
	v_mul_f32_e32 v130, 0x3d372713, v129
	v_mul_f32_e32 v130, v129, v130
	v_fma_f32 v130, v129, v130, v129
	v_mul_f32_e32 v130, 0x3fcc422a, v130
	v_mul_f32_e32 v130, 0xbfb8aa3b, v130
	v_exp_f32_e32 v130, v130
	s_nop 0
	v_add_f32_e32 v130, 1.0, v130
	v_rcp_f32_e32 v139, v130
	s_nop 0
	v_pk_mul_f32 v[138:139], v[128:129], v[138:139]
	v_lshlrev_b32_e32 v128, 16, v131
	v_and_b32_e32 v129, 0xffff0000, v131
	v_pk_fma_f32 v[128:129], v[140:141], v[128:129], v[26:27]
	s_nop 0
	v_mul_f32_e32 v130, 0x3d372713, v128
	v_mul_f32_e32 v131, 0x3d372713, v129
	v_mul_f32_e32 v130, v128, v130
	v_mul_f32_e32 v131, v129, v131
	v_fma_f32 v130, v128, v130, v128
	v_fma_f32 v131, v129, v131, v129
	v_mul_f32_e32 v130, 0x3fcc422a, v130
	v_mul_f32_e32 v131, 0x3fcc422a, v131
	v_mul_f32_e32 v130, 0xbfb8aa3b, v130
	v_mul_f32_e32 v131, 0xbfb8aa3b, v131
	v_exp_f32_e32 v130, v130
	v_exp_f32_e32 v131, v131
	v_add_f32_e32 v130, 1.0, v130
	v_add_f32_e32 v131, 1.0, v131
	v_rcp_f32_e32 v130, v130
	v_rcp_f32_e32 v131, v131
	s_nop 0
	v_pk_mul_f32 v[140:141], v[128:129], v[130:131]
	v_cvt_pk_bf16_f32 v130, v138, v139
	v_or_b32_e32 v138, v142, v187
	v_lshlrev_b32_e32 v138, 11, v138
	v_mov_b32_e32 v139, v145
	v_lshl_add_u64 v[138:139], s[90:91], 0, v[138:139]
	v_lshl_add_u64 v[138:139], v[138:139], 0, v[136:137]
	v_cvt_pk_bf16_f32 v128, v170, v171
	v_cvt_pk_bf16_f32 v129, v172, v173
	v_cvt_pk_bf16_f32 v131, v140, v141
	v_lshl_add_u64 v[138:139], v[138:139], 0, v[166:167]
	v_mov_b32_e32 v24, v128
	v_mov_b32_e32 v25, v129
	v_mov_b32_e32 v26, v130
	v_mov_b32_e32 v27, v131
	v_mov_b32_e32 v28, v138
	v_mov_b32_e32 v29, v139
	s_nop 1
	v_add_u32_e32 v130, 0xa0, v168
	v_mad_i64_i32 v[128:129], s[6:7], v130, s69, v[132:133]
	v_lshlrev_b32_e32 v130, 4, v130
	v_lshl_add_u64 v[138:139], v[128:129], 0, v[144:145]
	v_and_b32_e32 v142, 0x3ef0, v130
	s_waitcnt vmcnt(1)
	v_mov_b32_e32 v128, v190
	v_mov_b32_e32 v129, v191
	v_mov_b32_e32 v130, v192
	v_mov_b32_e32 v131, v193
	v_add_u32_e32 v214, 0xb0, v168
	v_mad_i64_i32 v[212:213], vcc, v214, s69, v[210:211]
	global_load_dwordx4 v[198:201], v[212:213], off
	v_lshlrev_b32_e32 v140, 16, v128
	v_and_b32_e32 v141, 0xffff0000, v128
	v_mov_b32_e32 v170, v202
	v_mov_b32_e32 v171, v203
	v_mov_b32_e32 v172, v204
	v_mov_b32_e32 v173, v205
	v_mov_b32_e32 v174, v206
	v_mov_b32_e32 v175, v207
	v_mov_b32_e32 v176, v208
	v_mov_b32_e32 v177, v209
	v_pk_fma_f32 v[140:141], v[174:175], v[140:141], v[36:37]
	s_nop 0
	v_mul_f32_e32 v128, 0x3d372713, v140
	v_mul_f32_e32 v128, v140, v128
	v_fma_f32 v128, v140, v128, v140
	v_mul_f32_e32 v128, 0x3fcc422a, v128
	v_mul_f32_e32 v128, 0xbfb8aa3b, v128
	v_exp_f32_e32 v128, v128
	s_nop 0
	v_add_f32_e32 v128, 1.0, v128
	v_rcp_f32_e32 v174, v128
	v_mul_f32_e32 v128, 0x3d372713, v141
	v_mul_f32_e32 v128, v141, v128
	v_fma_f32 v128, v141, v128, v141
	v_mul_f32_e32 v128, 0x3fcc422a, v128
	v_mul_f32_e32 v128, 0xbfb8aa3b, v128
	v_exp_f32_e32 v128, v128
	s_nop 0
	v_add_f32_e32 v128, 1.0, v128
	v_rcp_f32_e32 v175, v128
	v_lshlrev_b32_e32 v128, 16, v129
	v_and_b32_e32 v129, 0xffff0000, v129
	v_pk_fma_f32 v[128:129], v[176:177], v[128:129], v[38:39]
	v_pk_mul_f32 v[140:141], v[140:141], v[174:175]
	v_mul_f32_e32 v143, 0x3d372713, v128
	v_mul_f32_e32 v143, v128, v143
	v_fma_f32 v143, v128, v143, v128
	v_mul_f32_e32 v143, 0x3fcc422a, v143
	v_mul_f32_e32 v143, 0xbfb8aa3b, v143
	v_exp_f32_e32 v143, v143
	s_nop 0
	v_add_f32_e32 v143, 1.0, v143
	v_rcp_f32_e32 v174, v143
	v_mul_f32_e32 v143, 0x3d372713, v129
	v_mul_f32_e32 v143, v129, v143
	v_fma_f32 v143, v129, v143, v129
	v_mul_f32_e32 v143, 0x3fcc422a, v143
	v_mul_f32_e32 v143, 0xbfb8aa3b, v143
	v_exp_f32_e32 v143, v143
	s_nop 0
	v_add_f32_e32 v143, 1.0, v143
	v_rcp_f32_e32 v175, v143
	s_nop 0
	v_pk_mul_f32 v[174:175], v[128:129], v[174:175]
	v_lshlrev_b32_e32 v128, 16, v130
	v_and_b32_e32 v129, 0xffff0000, v130
	v_pk_fma_f32 v[128:129], v[170:171], v[128:129], v[32:33]
	s_nop 0
	v_mul_f32_e32 v130, 0x3d372713, v128
	v_mul_f32_e32 v130, v128, v130
	v_fma_f32 v130, v128, v130, v128
	v_mul_f32_e32 v130, 0x3fcc422a, v130
	v_mul_f32_e32 v130, 0xbfb8aa3b, v130
	v_exp_f32_e32 v130, v130
	s_nop 0
	v_add_f32_e32 v130, 1.0, v130
	v_rcp_f32_e32 v170, v130
	v_mul_f32_e32 v130, 0x3d372713, v129
	v_mul_f32_e32 v130, v129, v130
	v_fma_f32 v130, v129, v130, v129
	v_mul_f32_e32 v130, 0x3fcc422a, v130
	v_mul_f32_e32 v130, 0xbfb8aa3b, v130
	v_exp_f32_e32 v130, v130
	s_nop 0
	v_add_f32_e32 v130, 1.0, v130
	v_rcp_f32_e32 v171, v130
	s_nop 0
	v_pk_mul_f32 v[170:171], v[128:129], v[170:171]
	v_lshlrev_b32_e32 v128, 16, v131
	v_and_b32_e32 v129, 0xffff0000, v131
	v_pk_fma_f32 v[128:129], v[172:173], v[128:129], v[34:35]
	s_nop 0
	v_mul_f32_e32 v130, 0x3d372713, v128
	v_mul_f32_e32 v131, 0x3d372713, v129
	v_mul_f32_e32 v130, v128, v130
	v_mul_f32_e32 v131, v129, v131
	v_fma_f32 v130, v128, v130, v128
	v_fma_f32 v131, v129, v131, v129
	v_mul_f32_e32 v130, 0x3fcc422a, v130
	v_mul_f32_e32 v131, 0x3fcc422a, v131
	v_mul_f32_e32 v130, 0xbfb8aa3b, v130
	v_mul_f32_e32 v131, 0xbfb8aa3b, v131
	v_exp_f32_e32 v130, v130
	v_exp_f32_e32 v131, v131
	v_add_f32_e32 v130, 1.0, v130
	v_add_f32_e32 v131, 1.0, v131
	v_rcp_f32_e32 v130, v130
	v_rcp_f32_e32 v131, v131
	s_nop 0
	v_pk_mul_f32 v[172:173], v[128:129], v[130:131]
	v_cvt_pk_bf16_f32 v128, v140, v141
	v_or_b32_e32 v140, v142, v186
	v_lshlrev_b32_e32 v140, 11, v140
	v_mov_b32_e32 v141, v145
	v_lshl_add_u64 v[140:141], s[90:91], 0, v[140:141]
	v_lshl_add_u64 v[140:141], v[140:141], 0, v[136:137]
	v_cvt_pk_bf16_f32 v129, v174, v175
	v_cvt_pk_bf16_f32 v130, v170, v171
	v_cvt_pk_bf16_f32 v131, v172, v173
	v_lshl_add_u64 v[140:141], v[140:141], 0, v[166:167]
	v_mov_b32_e32 v32, v128
	v_mov_b32_e32 v33, v129
	v_mov_b32_e32 v34, v130
	v_mov_b32_e32 v35, v131
	v_mov_b32_e32 v36, v140
	v_mov_b32_e32 v37, v141
	s_waitcnt vmcnt(1)
	v_mov_b32_e32 v128, v194
	v_mov_b32_e32 v129, v195
	v_mov_b32_e32 v130, v196
	v_mov_b32_e32 v131, v197
	v_add_u32_e32 v214, 0xb0, v168
	v_mad_i64_i32 v[212:213], vcc, v214, s69, v[210:211]
	global_load_dwordx4 v[190:193], v[212:213], off offset:256
	v_lshlrev_b32_e32 v174, 16, v128
	v_and_b32_e32 v175, 0xffff0000, v128
	v_mov_b32_e32 v138, v202
	v_mov_b32_e32 v139, v203
	v_mov_b32_e32 v140, v204
	v_mov_b32_e32 v141, v205
	v_mov_b32_e32 v170, v206
	v_mov_b32_e32 v171, v207
	v_mov_b32_e32 v172, v208
	v_mov_b32_e32 v173, v209
	v_pk_fma_f32 v[170:171], v[170:171], v[174:175], v[12:13]
	s_nop 0
	v_mul_f32_e32 v128, 0x3d372713, v170
	v_mul_f32_e32 v128, v170, v128
	v_fma_f32 v128, v170, v128, v170
	v_mul_f32_e32 v128, 0x3fcc422a, v128
	v_mul_f32_e32 v128, 0xbfb8aa3b, v128
	v_exp_f32_e32 v128, v128
	s_nop 0
	v_add_f32_e32 v128, 1.0, v128
	v_rcp_f32_e32 v174, v128
	v_mul_f32_e32 v128, 0x3d372713, v171
	v_mul_f32_e32 v128, v171, v128
	v_fma_f32 v128, v171, v128, v171
	v_mul_f32_e32 v128, 0x3fcc422a, v128
	v_mul_f32_e32 v128, 0xbfb8aa3b, v128
	v_exp_f32_e32 v128, v128
	s_nop 0
	v_add_f32_e32 v128, 1.0, v128
	v_rcp_f32_e32 v175, v128
	v_lshlrev_b32_e32 v128, 16, v129
	v_and_b32_e32 v129, 0xffff0000, v129
	v_pk_fma_f32 v[128:129], v[172:173], v[128:129], v[14:15]
	v_pk_mul_f32 v[170:171], v[170:171], v[174:175]
	v_mul_f32_e32 v143, 0x3d372713, v128
	v_mul_f32_e32 v143, v128, v143
	v_fma_f32 v143, v128, v143, v128
	v_mul_f32_e32 v143, 0x3fcc422a, v143
	v_mul_f32_e32 v143, 0xbfb8aa3b, v143
	v_exp_f32_e32 v143, v143
	s_nop 0
	v_add_f32_e32 v143, 1.0, v143
	v_rcp_f32_e32 v172, v143
	v_mul_f32_e32 v143, 0x3d372713, v129
	v_mul_f32_e32 v143, v129, v143
	v_fma_f32 v143, v129, v143, v129
	v_mul_f32_e32 v143, 0x3fcc422a, v143
	v_mul_f32_e32 v143, 0xbfb8aa3b, v143
	v_exp_f32_e32 v143, v143
	s_nop 0
	v_add_f32_e32 v143, 1.0, v143
	v_rcp_f32_e32 v173, v143
	s_nop 0
	v_pk_mul_f32 v[172:173], v[128:129], v[172:173]
	v_lshlrev_b32_e32 v128, 16, v130
	v_and_b32_e32 v129, 0xffff0000, v130
	v_pk_fma_f32 v[128:129], v[138:139], v[128:129], v[8:9]
	s_nop 0
	v_mul_f32_e32 v130, 0x3d372713, v128
	v_mul_f32_e32 v130, v128, v130
	v_fma_f32 v130, v128, v130, v128
	v_mul_f32_e32 v130, 0x3fcc422a, v130
	v_mul_f32_e32 v130, 0xbfb8aa3b, v130
	v_exp_f32_e32 v130, v130
	s_nop 0
	v_add_f32_e32 v130, 1.0, v130
	v_rcp_f32_e32 v138, v130
	v_mul_f32_e32 v130, 0x3d372713, v129
	v_mul_f32_e32 v130, v129, v130
	v_fma_f32 v130, v129, v130, v129
	v_mul_f32_e32 v130, 0x3fcc422a, v130
	v_mul_f32_e32 v130, 0xbfb8aa3b, v130
	v_exp_f32_e32 v130, v130
	s_nop 0
	v_add_f32_e32 v130, 1.0, v130
	v_rcp_f32_e32 v139, v130
	s_nop 0
	v_pk_mul_f32 v[138:139], v[128:129], v[138:139]
	v_lshlrev_b32_e32 v128, 16, v131
	v_and_b32_e32 v129, 0xffff0000, v131
	v_pk_fma_f32 v[128:129], v[140:141], v[128:129], v[10:11]
	s_nop 0
	v_mul_f32_e32 v130, 0x3d372713, v128
	v_mul_f32_e32 v131, 0x3d372713, v129
	v_mul_f32_e32 v130, v128, v130
	v_mul_f32_e32 v131, v129, v131
	v_fma_f32 v130, v128, v130, v128
	v_fma_f32 v131, v129, v131, v129
	v_mul_f32_e32 v130, 0x3fcc422a, v130
	v_mul_f32_e32 v131, 0x3fcc422a, v131
	v_mul_f32_e32 v130, 0xbfb8aa3b, v130
	v_mul_f32_e32 v131, 0xbfb8aa3b, v131
	v_exp_f32_e32 v130, v130
	v_exp_f32_e32 v131, v131
	v_add_f32_e32 v130, 1.0, v130
	v_add_f32_e32 v131, 1.0, v131
	v_rcp_f32_e32 v130, v130
	v_rcp_f32_e32 v131, v131
	s_nop 0
	v_pk_mul_f32 v[140:141], v[128:129], v[130:131]
	v_cvt_pk_bf16_f32 v130, v138, v139
	v_or_b32_e32 v138, v142, v187
	v_lshlrev_b32_e32 v138, 11, v138
	v_mov_b32_e32 v139, v145
	v_lshl_add_u64 v[138:139], s[90:91], 0, v[138:139]
	v_lshl_add_u64 v[138:139], v[138:139], 0, v[136:137]
	v_cvt_pk_bf16_f32 v128, v170, v171
	v_cvt_pk_bf16_f32 v129, v172, v173
	v_cvt_pk_bf16_f32 v131, v140, v141
	v_lshl_add_u64 v[138:139], v[138:139], 0, v[166:167]
	v_mov_b32_e32 v8, v128
	v_mov_b32_e32 v9, v129
	v_mov_b32_e32 v10, v130
	v_mov_b32_e32 v11, v131
	v_mov_b32_e32 v12, v138
	v_mov_b32_e32 v13, v139
	s_nop 1
	v_add_u32_e32 v130, 0xb0, v168
	v_mad_i64_i32 v[128:129], s[6:7], v130, s69, v[132:133]
	v_lshlrev_b32_e32 v130, 4, v130
	v_lshl_add_u64 v[132:133], v[128:129], 0, v[144:145]
	v_and_b32_e32 v140, 0x3ff0, v130
	s_mov_b64 s[6:7], 0
	s_waitcnt vmcnt(1)
	v_mov_b32_e32 v128, v198
	v_mov_b32_e32 v129, v199
	v_mov_b32_e32 v130, v200
	v_mov_b32_e32 v131, v201
	v_lshlrev_b32_e32 v138, 16, v128
	v_and_b32_e32 v139, 0xffff0000, v128
	v_mov_b32_e32 v170, v202
	v_mov_b32_e32 v171, v203
	v_mov_b32_e32 v172, v204
	v_mov_b32_e32 v173, v205
	v_mov_b32_e32 v174, v206
	v_mov_b32_e32 v175, v207
	v_mov_b32_e32 v176, v208
	v_mov_b32_e32 v177, v209
	v_pk_fma_f32 v[138:139], v[174:175], v[138:139], v[20:21]
	s_nop 0
	v_mul_f32_e32 v128, 0x3d372713, v138
	v_mul_f32_e32 v128, v138, v128
	v_fma_f32 v128, v138, v128, v138
	v_mul_f32_e32 v128, 0x3fcc422a, v128
	v_mul_f32_e32 v128, 0xbfb8aa3b, v128
	v_exp_f32_e32 v128, v128
	s_nop 0
	v_add_f32_e32 v128, 1.0, v128
	v_rcp_f32_e32 v142, v128
	v_mul_f32_e32 v128, 0x3d372713, v139
	v_mul_f32_e32 v128, v139, v128
	v_fma_f32 v128, v139, v128, v139
	v_mul_f32_e32 v128, 0x3fcc422a, v128
	v_mul_f32_e32 v128, 0xbfb8aa3b, v128
	v_exp_f32_e32 v128, v128
	s_nop 0
	v_add_f32_e32 v128, 1.0, v128
	v_rcp_f32_e32 v143, v128
	v_lshlrev_b32_e32 v128, 16, v129
	v_and_b32_e32 v129, 0xffff0000, v129
	v_pk_fma_f32 v[128:129], v[176:177], v[128:129], v[22:23]
	v_pk_mul_f32 v[138:139], v[138:139], v[142:143]
	v_mul_f32_e32 v141, 0x3d372713, v128
	v_mul_f32_e32 v141, v128, v141
	v_fma_f32 v141, v128, v141, v128
	v_mul_f32_e32 v141, 0x3fcc422a, v141
	v_mul_f32_e32 v141, 0xbfb8aa3b, v141
	v_exp_f32_e32 v141, v141
	s_nop 0
	v_add_f32_e32 v141, 1.0, v141
	v_rcp_f32_e32 v142, v141
	v_mul_f32_e32 v141, 0x3d372713, v129
	v_mul_f32_e32 v141, v129, v141
	v_fma_f32 v141, v129, v141, v129
	v_mul_f32_e32 v141, 0x3fcc422a, v141
	v_mul_f32_e32 v141, 0xbfb8aa3b, v141
	v_exp_f32_e32 v141, v141
	s_nop 0
	v_add_f32_e32 v141, 1.0, v141
	v_rcp_f32_e32 v143, v141
	s_nop 0
	v_pk_mul_f32 v[142:143], v[128:129], v[142:143]
	v_lshlrev_b32_e32 v128, 16, v130
	v_and_b32_e32 v129, 0xffff0000, v130
	v_pk_fma_f32 v[128:129], v[170:171], v[128:129], v[16:17]
	s_nop 0
	v_mul_f32_e32 v130, 0x3d372713, v128
	v_mul_f32_e32 v130, v128, v130
	v_fma_f32 v130, v128, v130, v128
	v_mul_f32_e32 v130, 0x3fcc422a, v130
	v_mul_f32_e32 v130, 0xbfb8aa3b, v130
	v_exp_f32_e32 v130, v130
	s_nop 0
	v_add_f32_e32 v130, 1.0, v130
	v_rcp_f32_e32 v170, v130
	v_mul_f32_e32 v130, 0x3d372713, v129
	v_mul_f32_e32 v130, v129, v130
	v_fma_f32 v130, v129, v130, v129
	v_mul_f32_e32 v130, 0x3fcc422a, v130
	v_mul_f32_e32 v130, 0xbfb8aa3b, v130
	v_exp_f32_e32 v130, v130
	s_nop 0
	v_add_f32_e32 v130, 1.0, v130
	v_rcp_f32_e32 v171, v130
	s_nop 0
	v_pk_mul_f32 v[170:171], v[128:129], v[170:171]
	v_lshlrev_b32_e32 v128, 16, v131
	v_and_b32_e32 v129, 0xffff0000, v131
	v_pk_fma_f32 v[128:129], v[172:173], v[128:129], v[18:19]
	s_nop 0
	v_mul_f32_e32 v130, 0x3d372713, v128
	v_mul_f32_e32 v131, 0x3d372713, v129
	v_mul_f32_e32 v130, v128, v130
	v_mul_f32_e32 v131, v129, v131
	v_fma_f32 v130, v128, v130, v128
	v_fma_f32 v131, v129, v131, v129
	v_mul_f32_e32 v130, 0x3fcc422a, v130
	v_mul_f32_e32 v131, 0x3fcc422a, v131
	v_mul_f32_e32 v130, 0xbfb8aa3b, v130
	v_mul_f32_e32 v131, 0xbfb8aa3b, v131
	v_exp_f32_e32 v130, v130
	v_exp_f32_e32 v131, v131
	v_add_f32_e32 v130, 1.0, v130
	v_add_f32_e32 v131, 1.0, v131
	v_rcp_f32_e32 v130, v130
	v_rcp_f32_e32 v131, v131
	s_nop 0
	v_pk_mul_f32 v[172:173], v[128:129], v[130:131]
	v_cvt_pk_bf16_f32 v128, v138, v139
	v_or_b32_e32 v138, v140, v186
	v_lshlrev_b32_e32 v144, 11, v138
	v_lshl_add_u64 v[138:139], s[90:91], 0, v[144:145]
	v_lshl_add_u64 v[138:139], v[138:139], 0, v[136:137]
	v_cvt_pk_bf16_f32 v129, v142, v143
	v_cvt_pk_bf16_f32 v130, v170, v171
	v_cvt_pk_bf16_f32 v131, v172, v173
	v_lshl_add_u64 v[138:139], v[138:139], 0, v[166:167]
	v_mov_b32_e32 v16, v128
	v_mov_b32_e32 v17, v129
	v_mov_b32_e32 v18, v130
	v_mov_b32_e32 v19, v131
	v_mov_b32_e32 v20, v138
	v_mov_b32_e32 v21, v139
	s_waitcnt vmcnt(0)
	v_mov_b32_e32 v128, v190
	v_mov_b32_e32 v129, v191
	v_mov_b32_e32 v130, v192
	v_mov_b32_e32 v131, v193
	v_lshlrev_b32_e32 v138, 16, v128
	v_and_b32_e32 v139, 0xffff0000, v128
	v_mov_b32_e32 v170, v202
	v_mov_b32_e32 v171, v203
	v_mov_b32_e32 v172, v204
	v_mov_b32_e32 v173, v205
	v_mov_b32_e32 v132, v206
	v_mov_b32_e32 v133, v207
	v_mov_b32_e32 v134, v208
	v_mov_b32_e32 v135, v209
	v_pk_fma_f32 v[132:133], v[132:133], v[138:139], v[4:5]
	s_nop 0
	v_mul_f32_e32 v128, 0x3d372713, v132
	v_mul_f32_e32 v128, v132, v128
	v_fma_f32 v128, v132, v128, v132
	v_mul_f32_e32 v128, 0x3fcc422a, v128
	v_mul_f32_e32 v128, 0xbfb8aa3b, v128
	v_exp_f32_e32 v128, v128
	s_nop 0
	v_add_f32_e32 v128, 1.0, v128
	v_rcp_f32_e32 v138, v128
	v_mul_f32_e32 v128, 0x3d372713, v133
	v_mul_f32_e32 v128, v133, v128
	v_fma_f32 v128, v133, v128, v133
	v_mul_f32_e32 v128, 0x3fcc422a, v128
	v_mul_f32_e32 v128, 0xbfb8aa3b, v128
	v_exp_f32_e32 v128, v128
	s_nop 0
	v_add_f32_e32 v128, 1.0, v128
	v_rcp_f32_e32 v139, v128
	v_lshlrev_b32_e32 v128, 16, v129
	v_and_b32_e32 v129, 0xffff0000, v129
	v_pk_fma_f32 v[128:129], v[134:135], v[128:129], v[6:7]
	v_pk_mul_f32 v[132:133], v[132:133], v[138:139]
	v_mul_f32_e32 v134, 0x3d372713, v128
	v_mul_f32_e32 v135, 0x3d372713, v129
	v_mul_f32_e32 v134, v128, v134
	v_mul_f32_e32 v135, v129, v135
	v_fma_f32 v134, v128, v134, v128
	v_fma_f32 v135, v129, v135, v129
	v_mul_f32_e32 v134, 0x3fcc422a, v134
	v_mul_f32_e32 v135, 0x3fcc422a, v135
	v_mul_f32_e32 v134, 0xbfb8aa3b, v134
	v_mul_f32_e32 v135, 0xbfb8aa3b, v135
	v_exp_f32_e32 v134, v134
	v_exp_f32_e32 v135, v135
	v_add_f32_e32 v134, 1.0, v134
	v_add_f32_e32 v135, 1.0, v135
	v_rcp_f32_e32 v134, v134
	v_rcp_f32_e32 v135, v135
	s_nop 0
	v_pk_mul_f32 v[134:135], v[128:129], v[134:135]
	v_lshlrev_b32_e32 v128, 16, v130
	v_and_b32_e32 v129, 0xffff0000, v130
	v_pk_fma_f32 v[128:129], v[170:171], v[128:129], v[0:1]
	s_nop 0
	v_mul_f32_e32 v130, 0x3d372713, v128
	v_mul_f32_e32 v130, v128, v130
	v_fma_f32 v130, v128, v130, v128
	v_mul_f32_e32 v130, 0x3fcc422a, v130
	v_mul_f32_e32 v130, 0xbfb8aa3b, v130
	v_exp_f32_e32 v130, v130
	s_nop 0
	v_add_f32_e32 v130, 1.0, v130
	v_rcp_f32_e32 v138, v130
	v_mul_f32_e32 v130, 0x3d372713, v129
	v_mul_f32_e32 v130, v129, v130
	v_fma_f32 v130, v129, v130, v129
	v_mul_f32_e32 v130, 0x3fcc422a, v130
	v_mul_f32_e32 v130, 0xbfb8aa3b, v130
	v_exp_f32_e32 v130, v130
	s_nop 0
	v_add_f32_e32 v130, 1.0, v130
	v_rcp_f32_e32 v139, v130
	s_nop 0
	v_pk_mul_f32 v[138:139], v[128:129], v[138:139]
	v_lshlrev_b32_e32 v128, 16, v131
	v_and_b32_e32 v129, 0xffff0000, v131
	v_pk_fma_f32 v[128:129], v[172:173], v[128:129], v[2:3]
	s_nop 0
	v_mul_f32_e32 v130, 0x3d372713, v128
	v_mul_f32_e32 v131, 0x3d372713, v129
	v_mul_f32_e32 v130, v128, v130
	v_mul_f32_e32 v131, v129, v131
	v_fma_f32 v130, v128, v130, v128
	v_fma_f32 v131, v129, v131, v129
	v_mul_f32_e32 v130, 0x3fcc422a, v130
	v_mul_f32_e32 v131, 0x3fcc422a, v131
	v_mul_f32_e32 v130, 0xbfb8aa3b, v130
	v_mul_f32_e32 v131, 0xbfb8aa3b, v131
	v_exp_f32_e32 v130, v130
	v_exp_f32_e32 v131, v131
	v_add_f32_e32 v130, 1.0, v130
	v_add_f32_e32 v131, 1.0, v131
	v_rcp_f32_e32 v130, v130
	v_rcp_f32_e32 v131, v131
	s_nop 0
	v_pk_mul_f32 v[142:143], v[128:129], v[130:131]
	v_cvt_pk_bf16_f32 v128, v132, v133
	v_or_b32_e32 v132, v140, v187
	v_lshlrev_b32_e32 v144, 11, v132
	v_lshl_add_u64 v[132:133], s[90:91], 0, v[144:145]
	v_lshl_add_u64 v[132:133], v[132:133], 0, v[136:137]
	v_cvt_pk_bf16_f32 v129, v134, v135
	v_cvt_pk_bf16_f32 v130, v138, v139
	v_cvt_pk_bf16_f32 v131, v142, v143
	v_lshl_add_u64 v[132:133], v[132:133], 0, v[166:167]
	v_mov_b32_e32 v0, v128
	v_mov_b32_e32 v1, v129
	v_mov_b32_e32 v2, v130
	v_mov_b32_e32 v3, v131
	v_mov_b32_e32 v4, v132
	v_mov_b32_e32 v5, v133
	global_store_dwordx4 v[124:125], v[120:123], off offset:512
	global_store_dwordx4 v[108:109], v[104:107], off offset:512
	global_store_dwordx4 v[116:117], v[112:115], off offset:512
	global_store_dwordx4 v[92:93], v[88:91], off offset:512
	global_store_dwordx4 v[100:101], v[96:99], off offset:512
	global_store_dwordx4 v[76:77], v[72:75], off offset:512
	global_store_dwordx4 v[84:85], v[80:83], off offset:512
	global_store_dwordx4 v[68:69], v[64:67], off offset:512
	global_store_dwordx4 v[60:61], v[56:59], off offset:512
	global_store_dwordx4 v[44:45], v[40:43], off offset:512
	global_store_dwordx4 v[52:53], v[48:51], off offset:512
	global_store_dwordx4 v[28:29], v[24:27], off offset:512
	global_store_dwordx4 v[36:37], v[32:35], off offset:512
	global_store_dwordx4 v[12:13], v[8:11], off offset:512
	global_store_dwordx4 v[20:21], v[16:19], off offset:512
	global_store_dwordx4 v[4:5], v[0:3], off offset:512
	s_nop 1
